# memkv, phase 6, 7, 9, 11 GEMM loops: accumulator zeroing removed, first K iteration peeled with C = 0 first-touch MFMAs (same as phases 1 and 10); on v092
# baseline (speedup 1.0000x reference)
.LBB0_341:
	s_ashr_i32 s9, s8, 31
	v_cmp_lt_i64_e64 s[48:49], s[10:11], 64
	s_lshl_b64 s[10:11], s[8:9], 19
	s_add_u32 s10, s82, s10
	s_addc_u32 s11, s83, s11
	s_and_b64 s[12:13], s[48:49], exec
	s_cselect_b32 s9, s11, s45
	s_cselect_b32 s63, s10, s44
	s_ashr_i32 s7, s6, 31
	s_lshl_b64 s[12:13], s[6:7], 19
	s_add_u32 s12, s80, s12
	s_addc_u32 s13, s81, s13
	s_and_b64 s[48:49], s[48:49], exec
	s_cselect_b32 s7, s13, s47
	s_cselect_b32 s64, s12, s46
	s_add_u32 s44, s44, 0x40080
	s_addc_u32 s45, s45, 0
	s_add_u32 s65, s46, 0x100
	s_addc_u32 s66, s47, 0
	s_mov_b32 s67, -2
	ds_read_b128 v[146:149], v143
	ds_read_b128 v[150:153], v143 offset:1024
	ds_read_b128 v[154:157], v143 offset:2048
	ds_read_b128 v[158:161], v143 offset:3072
	s_add_u32 s46, s44, 0xfffc0080
	s_addc_u32 s47, s45, -1
	s_cmp_eq_u32 s67, 12
	s_cselect_b32 s49, s9, s47
	s_cselect_b32 s48, s63, s46
	s_cselect_b32 s47, s7, s66
	s_cselect_b32 s46, s64, s65
	v_lshl_add_u64 v[190:191], s[44:45], 0, v[136:137]
	s_add_i32 m0, s43, 0xc000
	ds_read_b128 v[162:165], v144
	ds_read_b128 v[166:169], v144 offset:1024
	ds_read_b128 v[170:173], v144 offset:2048
	ds_read_b128 v[174:177], v144 offset:3072
	ds_read_b128 v[178:181], v144 offset:4096
	ds_read_b128 v[182:185], v144 offset:5120
	ds_read_b128 v[186:189], v144 offset:6144
	ds_read_b128 v[196:199], v144 offset:7168
	global_load_lds_dwordx4 v[190:191], off
	v_lshl_add_u64 v[190:191], s[44:45], 0, v[138:139]
	s_add_i32 m0, s43, 0xe000
	s_nop 0
	global_load_lds_dwordx4 v[190:191], off
	s_waitcnt lgkmcnt(8)
	s_barrier
	s_waitcnt lgkmcnt(0)
	v_mfma_f32_16x16x32_bf16 v[124:127], v[146:149], v[162:165], 0
	v_mfma_f32_16x16x32_bf16 v[120:123], v[154:157], v[162:165], 0
	v_mfma_f32_16x16x32_bf16 v[108:111], v[146:149], v[170:173], 0
	v_mfma_f32_16x16x32_bf16 v[104:107], v[154:157], v[170:173], 0
	v_mfma_f32_16x16x32_bf16 v[92:95], v[146:149], v[178:181], 0
	v_mfma_f32_16x16x32_bf16 v[88:91], v[154:157], v[178:181], 0
	v_mfma_f32_16x16x32_bf16 v[76:79], v[146:149], v[186:189], 0
	v_mfma_f32_16x16x32_bf16 v[72:75], v[154:157], v[186:189], 0
	v_mfma_f32_16x16x32_bf16 v[124:127], v[150:153], v[166:169], v[124:127]
	v_mfma_f32_16x16x32_bf16 v[120:123], v[158:161], v[166:169], v[120:123]
	v_mfma_f32_16x16x32_bf16 v[108:111], v[150:153], v[174:177], v[108:111]
	v_mfma_f32_16x16x32_bf16 v[104:107], v[158:161], v[174:177], v[104:107]
	v_mfma_f32_16x16x32_bf16 v[92:95], v[150:153], v[182:185], v[92:95]
	v_mfma_f32_16x16x32_bf16 v[88:91], v[158:161], v[182:185], v[88:91]
	v_mfma_f32_16x16x32_bf16 v[76:79], v[150:153], v[196:199], v[76:79]
	v_mfma_f32_16x16x32_bf16 v[72:75], v[158:161], v[196:199], v[72:75]
	s_barrier
	s_add_i32 s84, s60, s50
	v_lshl_add_u64 v[190:191], s[46:47], 0, v[132:133]
	s_mov_b32 m0, s84
	ds_read_b128 v[200:203], v145
	ds_read_b128 v[204:207], v145 offset:1024
	ds_read_b128 v[208:211], v145 offset:2048
	ds_read_b128 v[212:215], v145 offset:3072
	global_load_lds_dwordx4 v[190:191], off
	v_lshl_add_u64 v[216:217], s[46:47], 0, v[128:129]
	s_add_i32 m0, s84, 0x2000
	s_nop 0
	global_load_lds_dwordx4 v[216:217], off
	s_barrier
	s_waitcnt lgkmcnt(0)
	v_mfma_f32_16x16x32_bf16 v[116:119], v[200:203], v[162:165], 0
	v_mfma_f32_16x16x32_bf16 v[112:115], v[208:211], v[162:165], 0
	v_mfma_f32_16x16x32_bf16 v[100:103], v[200:203], v[170:173], 0
	v_mfma_f32_16x16x32_bf16 v[96:99], v[208:211], v[170:173], 0
	v_mfma_f32_16x16x32_bf16 v[84:87], v[200:203], v[178:181], 0
	v_mfma_f32_16x16x32_bf16 v[80:83], v[208:211], v[178:181], 0
	v_mfma_f32_16x16x32_bf16 v[68:71], v[200:203], v[186:189], 0
	v_mfma_f32_16x16x32_bf16 v[64:67], v[208:211], v[186:189], 0
	v_mfma_f32_16x16x32_bf16 v[116:119], v[204:207], v[166:169], v[116:119]
	v_mfma_f32_16x16x32_bf16 v[112:115], v[212:215], v[166:169], v[112:115]
	v_mfma_f32_16x16x32_bf16 v[100:103], v[204:207], v[174:177], v[100:103]
	v_mfma_f32_16x16x32_bf16 v[96:99], v[212:215], v[174:177], v[96:99]
	v_mfma_f32_16x16x32_bf16 v[84:87], v[204:207], v[182:185], v[84:87]
	v_mfma_f32_16x16x32_bf16 v[80:83], v[212:215], v[182:185], v[80:83]
	v_mfma_f32_16x16x32_bf16 v[68:71], v[204:207], v[196:199], v[68:71]
	v_mfma_f32_16x16x32_bf16 v[64:67], v[212:215], v[196:199], v[64:67]
	s_mov_b32 m0, s43
	v_lshl_add_u64 v[218:219], s[48:49], 0, v[134:135]
	s_barrier
	ds_read_b128 v[162:165], v144 offset:16384
	ds_read_b128 v[166:169], v144 offset:17408
	ds_read_b128 v[170:173], v144 offset:18432
	ds_read_b128 v[174:177], v144 offset:19456
	ds_read_b128 v[178:181], v144 offset:20480
	ds_read_b128 v[182:185], v144 offset:21504
	ds_read_b128 v[186:189], v144 offset:22528
	ds_read_b128 v[196:199], v144 offset:23552
	global_load_lds_dwordx4 v[218:219], off
	v_lshl_add_u64 v[220:221], s[48:49], 0, v[130:131]
	s_mov_b32 m0, s52
	s_nop 0
	global_load_lds_dwordx4 v[220:221], off
	s_barrier
	s_waitcnt lgkmcnt(0)
	v_mfma_f32_16x16x32_bf16 v[60:63], v[146:149], v[162:165], 0
	v_mfma_f32_16x16x32_bf16 v[56:59], v[154:157], v[162:165], 0
	v_mfma_f32_16x16x32_bf16 v[44:47], v[146:149], v[170:173], 0
	v_mfma_f32_16x16x32_bf16 v[40:43], v[154:157], v[170:173], 0
	v_mfma_f32_16x16x32_bf16 v[28:31], v[146:149], v[178:181], 0
	v_mfma_f32_16x16x32_bf16 v[24:27], v[154:157], v[178:181], 0
	v_mfma_f32_16x16x32_bf16 v[12:15], v[146:149], v[186:189], 0
	v_mfma_f32_16x16x32_bf16 v[8:11], v[154:157], v[186:189], 0
	v_mfma_f32_16x16x32_bf16 v[60:63], v[150:153], v[166:169], v[60:63]
	v_mfma_f32_16x16x32_bf16 v[56:59], v[158:161], v[166:169], v[56:59]
	v_mfma_f32_16x16x32_bf16 v[44:47], v[150:153], v[174:177], v[44:47]
	v_mfma_f32_16x16x32_bf16 v[40:43], v[158:161], v[174:177], v[40:43]
	v_mfma_f32_16x16x32_bf16 v[28:31], v[150:153], v[182:185], v[28:31]
	v_mfma_f32_16x16x32_bf16 v[24:27], v[158:161], v[182:185], v[24:27]
	v_mfma_f32_16x16x32_bf16 v[12:15], v[150:153], v[196:199], v[12:15]
	v_mfma_f32_16x16x32_bf16 v[8:11], v[158:161], v[196:199], v[8:11]
	s_barrier
	s_add_u32 s84, s46, 0x10000
	s_addc_u32 s85, s47, 0
	s_add_i32 s89, s61, s50
	v_lshl_add_u64 v[146:147], s[84:85], 0, v[132:133]
	s_mov_b32 m0, s89
	s_nop 0
	global_load_lds_dwordx4 v[146:147], off
	v_lshl_add_u64 v[146:147], s[84:85], 0, v[128:129]
	s_add_i32 m0, s89, 0x2000
	s_nop 0
	global_load_lds_dwordx4 v[146:147], off
	s_waitcnt vmcnt(6)
	s_barrier
	v_mfma_f32_16x16x32_bf16 v[52:55], v[200:203], v[162:165], 0
	v_mfma_f32_16x16x32_bf16 v[48:51], v[208:211], v[162:165], 0
	v_mfma_f32_16x16x32_bf16 v[36:39], v[200:203], v[170:173], 0
	v_mfma_f32_16x16x32_bf16 v[32:35], v[208:211], v[170:173], 0
	v_mfma_f32_16x16x32_bf16 v[20:23], v[200:203], v[178:181], 0
	v_mfma_f32_16x16x32_bf16 v[16:19], v[208:211], v[178:181], 0
	v_mfma_f32_16x16x32_bf16 v[4:7], v[200:203], v[186:189], 0
	v_mfma_f32_16x16x32_bf16 v[0:3], v[208:211], v[186:189], 0
	v_mfma_f32_16x16x32_bf16 v[52:55], v[204:207], v[166:169], v[52:55]
	v_mfma_f32_16x16x32_bf16 v[48:51], v[212:215], v[166:169], v[48:51]
	v_mfma_f32_16x16x32_bf16 v[36:39], v[204:207], v[174:177], v[36:39]
	v_mfma_f32_16x16x32_bf16 v[32:35], v[212:215], v[174:177], v[32:35]
	v_mfma_f32_16x16x32_bf16 v[20:23], v[204:207], v[182:185], v[20:23]
	v_mfma_f32_16x16x32_bf16 v[16:19], v[212:215], v[182:185], v[16:19]
	v_mfma_f32_16x16x32_bf16 v[4:7], v[204:207], v[196:199], v[4:7]
	v_mfma_f32_16x16x32_bf16 v[0:3], v[212:215], v[196:199], v[0:3]
	s_add_i32 s84, 0, 0x18000
	v_add_u32_e32 v158, s84, v141
	s_barrier
	ds_read_b128 v[146:149], v158
	ds_read_b128 v[150:153], v158 offset:1024
	ds_read_b128 v[154:157], v158 offset:2048
	ds_read_b128 v[158:161], v158 offset:3072
	s_add_u32 s48, s48, 0x40000
	s_addc_u32 s49, s49, 0
	s_mov_b32 m0, s53
	v_lshl_add_u64 v[200:201], s[48:49], 0, v[134:135]
	ds_read_b128 v[162:165], v144 offset:32768
	ds_read_b128 v[166:169], v144 offset:33792
	ds_read_b128 v[170:173], v144 offset:34816
	ds_read_b128 v[174:177], v144 offset:35840
	ds_read_b128 v[178:181], v144 offset:36864
	ds_read_b128 v[182:185], v144 offset:37888
	ds_read_b128 v[186:189], v144 offset:38912
	ds_read_b128 v[196:199], v144 offset:39936
	global_load_lds_dwordx4 v[200:201], off
	v_lshl_add_u64 v[200:201], s[48:49], 0, v[130:131]
	s_mov_b32 m0, s54
	s_nop 0
	global_load_lds_dwordx4 v[200:201], off
	s_waitcnt lgkmcnt(8)
	s_barrier
	s_waitcnt lgkmcnt(0)
	v_mfma_f32_16x16x32_bf16 v[124:127], v[146:149], v[162:165], v[124:127]
	v_mfma_f32_16x16x32_bf16 v[120:123], v[154:157], v[162:165], v[120:123]
	v_mfma_f32_16x16x32_bf16 v[108:111], v[146:149], v[170:173], v[108:111]
	v_mfma_f32_16x16x32_bf16 v[104:107], v[154:157], v[170:173], v[104:107]
	v_mfma_f32_16x16x32_bf16 v[92:95], v[146:149], v[178:181], v[92:95]
	v_mfma_f32_16x16x32_bf16 v[88:91], v[154:157], v[178:181], v[88:91]
	v_mfma_f32_16x16x32_bf16 v[76:79], v[146:149], v[186:189], v[76:79]
	v_mfma_f32_16x16x32_bf16 v[72:75], v[154:157], v[186:189], v[72:75]
	v_mfma_f32_16x16x32_bf16 v[124:127], v[150:153], v[166:169], v[124:127]
	v_mfma_f32_16x16x32_bf16 v[120:123], v[158:161], v[166:169], v[120:123]
	v_mfma_f32_16x16x32_bf16 v[108:111], v[150:153], v[174:177], v[108:111]
	v_mfma_f32_16x16x32_bf16 v[104:107], v[158:161], v[174:177], v[104:107]
	v_mfma_f32_16x16x32_bf16 v[92:95], v[150:153], v[182:185], v[92:95]
	v_mfma_f32_16x16x32_bf16 v[88:91], v[158:161], v[182:185], v[88:91]
	v_mfma_f32_16x16x32_bf16 v[76:79], v[150:153], v[196:199], v[76:79]
	v_mfma_f32_16x16x32_bf16 v[72:75], v[158:161], v[196:199], v[72:75]
	s_barrier
	s_add_i32 s48, 0, 0x1c000
	s_add_i32 s49, s84, s50
	v_add_u32_e32 v195, s48, v141
	v_lshl_add_u64 v[190:191], v[190:191], 0, s[0:1]
	s_mov_b32 m0, s49
	ds_read_b128 v[200:203], v195
	ds_read_b128 v[204:207], v195 offset:1024
	ds_read_b128 v[208:211], v195 offset:2048
	ds_read_b128 v[212:215], v195 offset:3072
	global_load_lds_dwordx4 v[190:191], off
	v_lshl_add_u64 v[190:191], v[216:217], 0, s[0:1]
	s_add_i32 m0, s49, 0x2000
	s_nop 0
	global_load_lds_dwordx4 v[190:191], off
	s_barrier
	s_waitcnt lgkmcnt(0)
	v_mfma_f32_16x16x32_bf16 v[116:119], v[200:203], v[162:165], v[116:119]
	v_mfma_f32_16x16x32_bf16 v[112:115], v[208:211], v[162:165], v[112:115]
	v_mfma_f32_16x16x32_bf16 v[100:103], v[200:203], v[170:173], v[100:103]
	v_mfma_f32_16x16x32_bf16 v[96:99], v[208:211], v[170:173], v[96:99]
	v_mfma_f32_16x16x32_bf16 v[84:87], v[200:203], v[178:181], v[84:87]
	v_mfma_f32_16x16x32_bf16 v[80:83], v[208:211], v[178:181], v[80:83]
	v_mfma_f32_16x16x32_bf16 v[68:71], v[200:203], v[186:189], v[68:71]
	v_mfma_f32_16x16x32_bf16 v[64:67], v[208:211], v[186:189], v[64:67]
	v_mfma_f32_16x16x32_bf16 v[116:119], v[204:207], v[166:169], v[116:119]
	v_mfma_f32_16x16x32_bf16 v[112:115], v[212:215], v[166:169], v[112:115]
	v_mfma_f32_16x16x32_bf16 v[100:103], v[204:207], v[174:177], v[100:103]
	v_mfma_f32_16x16x32_bf16 v[96:99], v[212:215], v[174:177], v[96:99]
	v_mfma_f32_16x16x32_bf16 v[84:87], v[204:207], v[182:185], v[84:87]
	v_mfma_f32_16x16x32_bf16 v[80:83], v[212:215], v[182:185], v[80:83]
	v_mfma_f32_16x16x32_bf16 v[68:71], v[204:207], v[196:199], v[68:71]
	v_mfma_f32_16x16x32_bf16 v[64:67], v[212:215], v[196:199], v[64:67]
	s_mov_b32 m0, s57
	v_lshl_add_u64 v[190:191], v[218:219], 0, s[0:1]
	s_barrier
	ds_read_b128 v[162:165], v144 offset:49152
	ds_read_b128 v[166:169], v144 offset:50176
	ds_read_b128 v[170:173], v144 offset:51200
	ds_read_b128 v[174:177], v144 offset:52224
	ds_read_b128 v[178:181], v144 offset:53248
	ds_read_b128 v[182:185], v144 offset:54272
	ds_read_b128 v[186:189], v144 offset:55296
	ds_read_b128 v[196:199], v144 offset:56320
	global_load_lds_dwordx4 v[190:191], off
	v_lshl_add_u64 v[190:191], v[220:221], 0, s[0:1]
	s_mov_b32 m0, s58
	s_nop 0
	global_load_lds_dwordx4 v[190:191], off
	s_barrier
	s_waitcnt lgkmcnt(0)
	v_mfma_f32_16x16x32_bf16 v[60:63], v[146:149], v[162:165], v[60:63]
	v_mfma_f32_16x16x32_bf16 v[56:59], v[154:157], v[162:165], v[56:59]
	v_mfma_f32_16x16x32_bf16 v[44:47], v[146:149], v[170:173], v[44:47]
	v_mfma_f32_16x16x32_bf16 v[40:43], v[154:157], v[170:173], v[40:43]
	v_mfma_f32_16x16x32_bf16 v[28:31], v[146:149], v[178:181], v[28:31]
	v_mfma_f32_16x16x32_bf16 v[24:27], v[154:157], v[178:181], v[24:27]
	v_mfma_f32_16x16x32_bf16 v[12:15], v[146:149], v[186:189], v[12:15]
	v_mfma_f32_16x16x32_bf16 v[8:11], v[154:157], v[186:189], v[8:11]
	v_mfma_f32_16x16x32_bf16 v[60:63], v[150:153], v[166:169], v[60:63]
	v_mfma_f32_16x16x32_bf16 v[56:59], v[158:161], v[166:169], v[56:59]
	v_mfma_f32_16x16x32_bf16 v[44:47], v[150:153], v[174:177], v[44:47]
	v_mfma_f32_16x16x32_bf16 v[40:43], v[158:161], v[174:177], v[40:43]
	v_mfma_f32_16x16x32_bf16 v[28:31], v[150:153], v[182:185], v[28:31]
	v_mfma_f32_16x16x32_bf16 v[24:27], v[158:161], v[182:185], v[24:27]
	v_mfma_f32_16x16x32_bf16 v[12:15], v[150:153], v[196:199], v[12:15]
	v_mfma_f32_16x16x32_bf16 v[8:11], v[158:161], v[196:199], v[8:11]
	s_barrier
	s_add_u32 s46, s46, 0x10080
	s_addc_u32 s47, s47, 0
	s_add_i32 s48, s48, s50
	v_lshl_add_u64 v[146:147], s[46:47], 0, v[132:133]
	s_mov_b32 m0, s48
	s_nop 0
	global_load_lds_dwordx4 v[146:147], off
	v_lshl_add_u64 v[146:147], s[46:47], 0, v[128:129]
	s_add_i32 m0, s48, 0x2000
	s_nop 0
	global_load_lds_dwordx4 v[146:147], off
	s_waitcnt vmcnt(6)
	s_barrier
	v_mfma_f32_16x16x32_bf16 v[52:55], v[200:203], v[162:165], v[52:55]
	v_mfma_f32_16x16x32_bf16 v[48:51], v[208:211], v[162:165], v[48:51]
	v_mfma_f32_16x16x32_bf16 v[36:39], v[200:203], v[170:173], v[36:39]
	v_mfma_f32_16x16x32_bf16 v[32:35], v[208:211], v[170:173], v[32:35]
	v_mfma_f32_16x16x32_bf16 v[20:23], v[200:203], v[178:181], v[20:23]
	v_mfma_f32_16x16x32_bf16 v[16:19], v[208:211], v[178:181], v[16:19]
	v_mfma_f32_16x16x32_bf16 v[4:7], v[200:203], v[186:189], v[4:7]
	v_mfma_f32_16x16x32_bf16 v[0:3], v[208:211], v[186:189], v[0:3]
	v_mfma_f32_16x16x32_bf16 v[52:55], v[204:207], v[166:169], v[52:55]
	v_mfma_f32_16x16x32_bf16 v[48:51], v[212:215], v[166:169], v[48:51]
	v_mfma_f32_16x16x32_bf16 v[36:39], v[204:207], v[174:177], v[36:39]
	v_mfma_f32_16x16x32_bf16 v[32:35], v[212:215], v[174:177], v[32:35]
	v_mfma_f32_16x16x32_bf16 v[20:23], v[204:207], v[182:185], v[20:23]
	v_mfma_f32_16x16x32_bf16 v[16:19], v[212:215], v[182:185], v[16:19]
	v_mfma_f32_16x16x32_bf16 v[4:7], v[204:207], v[196:199], v[4:7]
	v_mfma_f32_16x16x32_bf16 v[0:3], v[212:215], v[196:199], v[0:3]
	s_add_i32 s67, s67, 2
	s_add_u32 s44, s44, 0x100
	s_addc_u32 s45, s45, 0
	s_add_u32 s65, s65, 0x100
	s_addc_u32 s66, s66, 0
	s_cmp_gt_u32 s67, 13
	s_barrier
	s_cbranch_scc0 .LBB0_342

.LBB0_739:
	s_ashr_i32 s57, s56, 31
	v_cmp_lt_i64_e32 vcc, s[58:59], v[208:209]
	s_lshl_b64 s[58:59], s[56:57], 19
	s_add_u32 s58, s68, s58
	s_addc_u32 s59, s69, s59
	s_and_b64 s[60:61], vcc, exec
	s_cselect_b32 s9, s59, s11
	s_cselect_b32 s13, s58, s10
	s_ashr_i32 s55, s54, 31
	s_lshl_b64 s[60:61], s[54:55], 19
	s_add_u32 s60, s76, s60
	s_addc_u32 s61, s77, s61
	s_and_b64 s[64:65], vcc, exec
	s_cselect_b32 s17, s61, s63
	s_cselect_b32 s44, s60, s62
	s_add_u32 s10, s10, 0x40080
	s_addc_u32 s11, s11, 0
	s_add_u32 s55, s62, 0x100
	s_addc_u32 s57, s63, 0
	s_mov_b32 s92, -2
	s_waitcnt lgkmcnt(0)
	ds_read_b128 v[64:67], v221
	ds_read_b128 v[68:71], v221 offset:1024
	ds_read_b128 v[84:87], v221 offset:2048
	ds_read_b128 v[92:95], v221 offset:3072
	s_add_u32 s28, s10, 0xfffc0080
	s_addc_u32 s29, s11, -1
	s_cmp_eq_u32 s92, 12
	s_cselect_b32 s65, s9, s29
	s_cselect_b32 s64, s13, s28
	s_cselect_b32 s63, s17, s57
	s_cselect_b32 s62, s44, s55
	v_lshl_add_u64 v[176:177], s[10:11], 0, v[204:205]
	s_add_i32 m0, s78, 0xc000
	ds_read_b128 v[144:147], v222
	ds_read_b128 v[148:151], v222 offset:1024
	ds_read_b128 v[152:155], v222 offset:2048
	ds_read_b128 v[156:159], v222 offset:3072
	ds_read_b128 v[160:163], v222 offset:4096
	ds_read_b128 v[164:167], v222 offset:5120
	ds_read_b128 v[168:171], v222 offset:6144
	ds_read_b128 v[172:175], v222 offset:7168
	global_load_lds_dwordx4 v[176:177], off
	v_lshl_add_u64 v[176:177], s[10:11], 0, v[206:207]
	s_add_i32 m0, s78, 0xe000
	s_nop 0
	global_load_lds_dwordx4 v[176:177], off
	s_waitcnt lgkmcnt(8)
	s_barrier
	s_waitcnt lgkmcnt(0)
	v_mfma_f32_16x16x32_bf16 v[140:143], v[64:67], v[144:147], 0
	v_mfma_f32_16x16x32_bf16 v[136:139], v[84:87], v[144:147], 0
	v_mfma_f32_16x16x32_bf16 v[124:127], v[64:67], v[152:155], 0
	v_mfma_f32_16x16x32_bf16 v[120:123], v[84:87], v[152:155], 0
	v_mfma_f32_16x16x32_bf16 v[108:111], v[64:67], v[160:163], 0
	v_mfma_f32_16x16x32_bf16 v[104:107], v[84:87], v[160:163], 0
	v_mfma_f32_16x16x32_bf16 v[88:91], v[64:67], v[168:171], 0
	v_mfma_f32_16x16x32_bf16 v[80:83], v[84:87], v[168:171], 0
	v_mfma_f32_16x16x32_bf16 v[140:143], v[68:71], v[148:151], v[140:143]
	v_mfma_f32_16x16x32_bf16 v[136:139], v[92:95], v[148:151], v[136:139]
	v_mfma_f32_16x16x32_bf16 v[124:127], v[68:71], v[156:159], v[124:127]
	v_mfma_f32_16x16x32_bf16 v[120:123], v[92:95], v[156:159], v[120:123]
	v_mfma_f32_16x16x32_bf16 v[108:111], v[68:71], v[164:167], v[108:111]
	v_mfma_f32_16x16x32_bf16 v[104:107], v[92:95], v[164:167], v[104:107]
	v_mfma_f32_16x16x32_bf16 v[88:91], v[68:71], v[172:175], v[88:91]
	v_mfma_f32_16x16x32_bf16 v[80:83], v[92:95], v[172:175], v[80:83]
	s_barrier
	s_add_i32 s28, s89, s67
	v_lshl_add_u64 v[212:213], s[62:63], 0, v[198:199]
	s_mov_b32 m0, s28
	ds_read_b128 v[176:179], v223
	ds_read_b128 v[180:183], v223 offset:1024
	ds_read_b128 v[184:187], v223 offset:2048
	ds_read_b128 v[188:191], v223 offset:3072
	global_load_lds_dwordx4 v[212:213], off
	v_lshl_add_u64 v[214:215], s[62:63], 0, v[202:203]
	s_add_i32 m0, s28, 0x2000
	s_nop 0
	global_load_lds_dwordx4 v[214:215], off
	s_barrier
	s_waitcnt lgkmcnt(0)
	v_mfma_f32_16x16x32_bf16 v[132:135], v[176:179], v[144:147], 0
	v_mfma_f32_16x16x32_bf16 v[128:131], v[184:187], v[144:147], 0
	v_mfma_f32_16x16x32_bf16 v[116:119], v[176:179], v[152:155], 0
	v_mfma_f32_16x16x32_bf16 v[112:115], v[184:187], v[152:155], 0
	v_mfma_f32_16x16x32_bf16 v[100:103], v[176:179], v[160:163], 0
	v_mfma_f32_16x16x32_bf16 v[96:99], v[184:187], v[160:163], 0
	v_mfma_f32_16x16x32_bf16 v[76:79], v[176:179], v[168:171], 0
	v_mfma_f32_16x16x32_bf16 v[72:75], v[184:187], v[168:171], 0
	v_mfma_f32_16x16x32_bf16 v[132:135], v[180:183], v[148:151], v[132:135]
	v_mfma_f32_16x16x32_bf16 v[128:131], v[188:191], v[148:151], v[128:131]
	v_mfma_f32_16x16x32_bf16 v[116:119], v[180:183], v[156:159], v[116:119]
	v_mfma_f32_16x16x32_bf16 v[112:115], v[188:191], v[156:159], v[112:115]
	v_mfma_f32_16x16x32_bf16 v[100:103], v[180:183], v[164:167], v[100:103]
	v_mfma_f32_16x16x32_bf16 v[96:99], v[188:191], v[164:167], v[96:99]
	v_mfma_f32_16x16x32_bf16 v[76:79], v[180:183], v[172:175], v[76:79]
	v_mfma_f32_16x16x32_bf16 v[72:75], v[188:191], v[172:175], v[72:75]
	s_mov_b32 m0, s78
	v_lshl_add_u64 v[216:217], s[64:65], 0, v[196:197]
	s_barrier
	ds_read_b128 v[144:147], v222 offset:16384
	ds_read_b128 v[148:151], v222 offset:17408
	ds_read_b128 v[152:155], v222 offset:18432
	ds_read_b128 v[156:159], v222 offset:19456
	ds_read_b128 v[160:163], v222 offset:20480
	ds_read_b128 v[164:167], v222 offset:21504
	ds_read_b128 v[168:171], v222 offset:22528
	ds_read_b128 v[172:175], v222 offset:23552
	global_load_lds_dwordx4 v[216:217], off
	v_lshl_add_u64 v[226:227], s[64:65], 0, v[200:201]
	s_mov_b32 m0, s79
	s_nop 0
	global_load_lds_dwordx4 v[226:227], off
	s_barrier
	s_waitcnt lgkmcnt(0)
	v_mfma_f32_16x16x32_bf16 v[60:63], v[64:67], v[144:147], 0
	v_mfma_f32_16x16x32_bf16 v[56:59], v[84:87], v[144:147], 0
	v_mfma_f32_16x16x32_bf16 v[44:47], v[64:67], v[152:155], 0
	v_mfma_f32_16x16x32_bf16 v[40:43], v[84:87], v[152:155], 0
	v_mfma_f32_16x16x32_bf16 v[28:31], v[64:67], v[160:163], 0
	v_mfma_f32_16x16x32_bf16 v[24:27], v[84:87], v[160:163], 0
	v_mfma_f32_16x16x32_bf16 v[12:15], v[64:67], v[168:171], 0
	v_mfma_f32_16x16x32_bf16 v[8:11], v[84:87], v[168:171], 0
	v_mfma_f32_16x16x32_bf16 v[60:63], v[68:71], v[148:151], v[60:63]
	v_mfma_f32_16x16x32_bf16 v[56:59], v[92:95], v[148:151], v[56:59]
	v_mfma_f32_16x16x32_bf16 v[44:47], v[68:71], v[156:159], v[44:47]
	v_mfma_f32_16x16x32_bf16 v[40:43], v[92:95], v[156:159], v[40:43]
	v_mfma_f32_16x16x32_bf16 v[28:31], v[68:71], v[164:167], v[28:31]
	v_mfma_f32_16x16x32_bf16 v[24:27], v[92:95], v[164:167], v[24:27]
	v_mfma_f32_16x16x32_bf16 v[12:15], v[68:71], v[172:175], v[12:15]
	v_mfma_f32_16x16x32_bf16 v[8:11], v[92:95], v[172:175], v[8:11]
	s_barrier
	s_add_u32 s94, s62, 0x10000
	s_addc_u32 s95, s63, 0
	s_add_i32 s28, s90, s67
	v_lshl_add_u64 v[64:65], s[94:95], 0, v[198:199]
	s_mov_b32 m0, s28
	s_nop 0
	global_load_lds_dwordx4 v[64:65], off
	v_lshl_add_u64 v[64:65], s[94:95], 0, v[202:203]
	s_add_i32 m0, s28, 0x2000
	s_nop 0
	global_load_lds_dwordx4 v[64:65], off
	s_waitcnt vmcnt(6)
	s_barrier
	v_mfma_f32_16x16x32_bf16 v[52:55], v[176:179], v[144:147], 0
	v_mfma_f32_16x16x32_bf16 v[48:51], v[184:187], v[144:147], 0
	v_mfma_f32_16x16x32_bf16 v[36:39], v[176:179], v[152:155], 0
	v_mfma_f32_16x16x32_bf16 v[32:35], v[184:187], v[152:155], 0
	v_mfma_f32_16x16x32_bf16 v[20:23], v[176:179], v[160:163], 0
	v_mfma_f32_16x16x32_bf16 v[16:19], v[184:187], v[160:163], 0
	v_mfma_f32_16x16x32_bf16 v[4:7], v[176:179], v[168:171], 0
	v_mfma_f32_16x16x32_bf16 v[0:3], v[184:187], v[168:171], 0
	v_mfma_f32_16x16x32_bf16 v[52:55], v[180:183], v[148:151], v[52:55]
	v_mfma_f32_16x16x32_bf16 v[48:51], v[188:191], v[148:151], v[48:51]
	v_mfma_f32_16x16x32_bf16 v[36:39], v[180:183], v[156:159], v[36:39]
	v_mfma_f32_16x16x32_bf16 v[32:35], v[188:191], v[156:159], v[32:35]
	v_mfma_f32_16x16x32_bf16 v[20:23], v[180:183], v[164:167], v[20:23]
	v_mfma_f32_16x16x32_bf16 v[16:19], v[188:191], v[164:167], v[16:19]
	v_mfma_f32_16x16x32_bf16 v[4:7], v[180:183], v[172:175], v[4:7]
	v_mfma_f32_16x16x32_bf16 v[0:3], v[188:191], v[172:175], v[0:3]
	s_add_i32 s28, 0, 0x18000
	v_add_u32_e32 v92, s28, v218
	s_barrier
	ds_read_b128 v[64:67], v92
	ds_read_b128 v[68:71], v92 offset:1024
	ds_read_b128 v[84:87], v92 offset:2048
	ds_read_b128 v[92:95], v92 offset:3072
	s_add_u32 s64, s64, 0x40000
	s_addc_u32 s65, s65, 0
	s_mov_b32 m0, s80
	v_lshl_add_u64 v[176:177], s[64:65], 0, v[196:197]
	ds_read_b128 v[144:147], v222 offset:32768
	ds_read_b128 v[148:151], v222 offset:33792
	ds_read_b128 v[152:155], v222 offset:34816
	ds_read_b128 v[156:159], v222 offset:35840
	ds_read_b128 v[160:163], v222 offset:36864
	ds_read_b128 v[164:167], v222 offset:37888
	ds_read_b128 v[168:171], v222 offset:38912
	ds_read_b128 v[172:175], v222 offset:39936
	global_load_lds_dwordx4 v[176:177], off
	v_lshl_add_u64 v[176:177], s[64:65], 0, v[200:201]
	s_mov_b32 m0, s81
	s_nop 0
	global_load_lds_dwordx4 v[176:177], off
	s_waitcnt lgkmcnt(8)
	s_barrier
	s_waitcnt lgkmcnt(0)
	v_mfma_f32_16x16x32_bf16 v[140:143], v[64:67], v[144:147], v[140:143]
	v_mfma_f32_16x16x32_bf16 v[136:139], v[84:87], v[144:147], v[136:139]
	v_mfma_f32_16x16x32_bf16 v[124:127], v[64:67], v[152:155], v[124:127]
	v_mfma_f32_16x16x32_bf16 v[120:123], v[84:87], v[152:155], v[120:123]
	v_mfma_f32_16x16x32_bf16 v[108:111], v[64:67], v[160:163], v[108:111]
	v_mfma_f32_16x16x32_bf16 v[104:107], v[84:87], v[160:163], v[104:107]
	v_mfma_f32_16x16x32_bf16 v[88:91], v[64:67], v[168:171], v[88:91]
	v_mfma_f32_16x16x32_bf16 v[80:83], v[84:87], v[168:171], v[80:83]
	v_mfma_f32_16x16x32_bf16 v[140:143], v[68:71], v[148:151], v[140:143]
	v_mfma_f32_16x16x32_bf16 v[136:139], v[92:95], v[148:151], v[136:139]
	v_mfma_f32_16x16x32_bf16 v[124:127], v[68:71], v[156:159], v[124:127]
	v_mfma_f32_16x16x32_bf16 v[120:123], v[92:95], v[156:159], v[120:123]
	v_mfma_f32_16x16x32_bf16 v[108:111], v[68:71], v[164:167], v[108:111]
	v_mfma_f32_16x16x32_bf16 v[104:107], v[92:95], v[164:167], v[104:107]
	v_mfma_f32_16x16x32_bf16 v[88:91], v[68:71], v[172:175], v[88:91]
	v_mfma_f32_16x16x32_bf16 v[80:83], v[92:95], v[172:175], v[80:83]
	s_barrier
	s_add_i32 s29, 0, 0x1c000
	s_add_i32 s28, s28, s67
	v_add_u32_e32 v188, s29, v218
	v_lshl_add_u64 v[212:213], v[212:213], 0, s[52:53]
	s_mov_b32 m0, s28
	ds_read_b128 v[176:179], v188
	ds_read_b128 v[180:183], v188 offset:1024
	ds_read_b128 v[184:187], v188 offset:2048
	ds_read_b128 v[188:191], v188 offset:3072
	global_load_lds_dwordx4 v[212:213], off
	v_lshl_add_u64 v[212:213], v[214:215], 0, s[52:53]
	s_add_i32 m0, s28, 0x2000
	s_nop 0
	global_load_lds_dwordx4 v[212:213], off
	s_barrier
	s_waitcnt lgkmcnt(0)
	v_mfma_f32_16x16x32_bf16 v[132:135], v[176:179], v[144:147], v[132:135]
	v_mfma_f32_16x16x32_bf16 v[128:131], v[184:187], v[144:147], v[128:131]
	v_mfma_f32_16x16x32_bf16 v[116:119], v[176:179], v[152:155], v[116:119]
	v_mfma_f32_16x16x32_bf16 v[112:115], v[184:187], v[152:155], v[112:115]
	v_mfma_f32_16x16x32_bf16 v[100:103], v[176:179], v[160:163], v[100:103]
	v_mfma_f32_16x16x32_bf16 v[96:99], v[184:187], v[160:163], v[96:99]
	v_mfma_f32_16x16x32_bf16 v[76:79], v[176:179], v[168:171], v[76:79]
	v_mfma_f32_16x16x32_bf16 v[72:75], v[184:187], v[168:171], v[72:75]
	v_mfma_f32_16x16x32_bf16 v[132:135], v[180:183], v[148:151], v[132:135]
	v_mfma_f32_16x16x32_bf16 v[128:131], v[188:191], v[148:151], v[128:131]
	v_mfma_f32_16x16x32_bf16 v[116:119], v[180:183], v[156:159], v[116:119]
	v_mfma_f32_16x16x32_bf16 v[112:115], v[188:191], v[156:159], v[112:115]
	v_mfma_f32_16x16x32_bf16 v[100:103], v[180:183], v[164:167], v[100:103]
	v_mfma_f32_16x16x32_bf16 v[96:99], v[188:191], v[164:167], v[96:99]
	v_mfma_f32_16x16x32_bf16 v[76:79], v[180:183], v[172:175], v[76:79]
	v_mfma_f32_16x16x32_bf16 v[72:75], v[188:191], v[172:175], v[72:75]
	s_mov_b32 m0, s85
	v_lshl_add_u64 v[212:213], v[216:217], 0, s[52:53]
	s_barrier
	ds_read_b128 v[144:147], v222 offset:49152
	ds_read_b128 v[148:151], v222 offset:50176
	ds_read_b128 v[152:155], v222 offset:51200
	ds_read_b128 v[156:159], v222 offset:52224
	ds_read_b128 v[160:163], v222 offset:53248
	ds_read_b128 v[164:167], v222 offset:54272
	ds_read_b128 v[168:171], v222 offset:55296
	ds_read_b128 v[172:175], v222 offset:56320
	global_load_lds_dwordx4 v[212:213], off
	v_lshl_add_u64 v[212:213], v[226:227], 0, s[52:53]
	s_mov_b32 m0, s87
	s_nop 0
	global_load_lds_dwordx4 v[212:213], off
	s_barrier
	s_waitcnt lgkmcnt(0)
	v_mfma_f32_16x16x32_bf16 v[60:63], v[64:67], v[144:147], v[60:63]
	v_mfma_f32_16x16x32_bf16 v[56:59], v[84:87], v[144:147], v[56:59]
	v_mfma_f32_16x16x32_bf16 v[44:47], v[64:67], v[152:155], v[44:47]
	v_mfma_f32_16x16x32_bf16 v[40:43], v[84:87], v[152:155], v[40:43]
	v_mfma_f32_16x16x32_bf16 v[28:31], v[64:67], v[160:163], v[28:31]
	v_mfma_f32_16x16x32_bf16 v[24:27], v[84:87], v[160:163], v[24:27]
	v_mfma_f32_16x16x32_bf16 v[12:15], v[64:67], v[168:171], v[12:15]
	v_mfma_f32_16x16x32_bf16 v[8:11], v[84:87], v[168:171], v[8:11]
	v_mfma_f32_16x16x32_bf16 v[60:63], v[68:71], v[148:151], v[60:63]
	v_mfma_f32_16x16x32_bf16 v[56:59], v[92:95], v[148:151], v[56:59]
	v_mfma_f32_16x16x32_bf16 v[44:47], v[68:71], v[156:159], v[44:47]
	v_mfma_f32_16x16x32_bf16 v[40:43], v[92:95], v[156:159], v[40:43]
	v_mfma_f32_16x16x32_bf16 v[28:31], v[68:71], v[164:167], v[28:31]
	v_mfma_f32_16x16x32_bf16 v[24:27], v[92:95], v[164:167], v[24:27]
	v_mfma_f32_16x16x32_bf16 v[12:15], v[68:71], v[172:175], v[12:15]
	v_mfma_f32_16x16x32_bf16 v[8:11], v[92:95], v[172:175], v[8:11]
	s_barrier
	s_add_u32 s62, s62, 0x10080
	s_addc_u32 s63, s63, 0
	s_add_i32 s28, s29, s67
	v_lshl_add_u64 v[64:65], s[62:63], 0, v[198:199]
	s_mov_b32 m0, s28
	s_nop 0
	global_load_lds_dwordx4 v[64:65], off
	v_lshl_add_u64 v[64:65], s[62:63], 0, v[202:203]
	s_add_i32 m0, s28, 0x2000
	s_nop 0
	global_load_lds_dwordx4 v[64:65], off
	s_waitcnt vmcnt(6)
	s_barrier
	v_mfma_f32_16x16x32_bf16 v[52:55], v[176:179], v[144:147], v[52:55]
	v_mfma_f32_16x16x32_bf16 v[48:51], v[184:187], v[144:147], v[48:51]
	v_mfma_f32_16x16x32_bf16 v[36:39], v[176:179], v[152:155], v[36:39]
	v_mfma_f32_16x16x32_bf16 v[32:35], v[184:187], v[152:155], v[32:35]
	v_mfma_f32_16x16x32_bf16 v[20:23], v[176:179], v[160:163], v[20:23]
	v_mfma_f32_16x16x32_bf16 v[16:19], v[184:187], v[160:163], v[16:19]
	v_mfma_f32_16x16x32_bf16 v[4:7], v[176:179], v[168:171], v[4:7]
	v_mfma_f32_16x16x32_bf16 v[0:3], v[184:187], v[168:171], v[0:3]
	v_mfma_f32_16x16x32_bf16 v[52:55], v[180:183], v[148:151], v[52:55]
	v_mfma_f32_16x16x32_bf16 v[48:51], v[188:191], v[148:151], v[48:51]
	v_mfma_f32_16x16x32_bf16 v[36:39], v[180:183], v[156:159], v[36:39]
	v_mfma_f32_16x16x32_bf16 v[32:35], v[188:191], v[156:159], v[32:35]
	v_mfma_f32_16x16x32_bf16 v[20:23], v[180:183], v[164:167], v[20:23]
	v_mfma_f32_16x16x32_bf16 v[16:19], v[188:191], v[164:167], v[16:19]
	v_mfma_f32_16x16x32_bf16 v[4:7], v[180:183], v[172:175], v[4:7]
	v_mfma_f32_16x16x32_bf16 v[0:3], v[188:191], v[172:175], v[0:3]
	s_add_i32 s92, s92, 2
	s_add_u32 s10, s10, 0x100
	s_addc_u32 s11, s11, 0
	s_add_u32 s55, s55, 0x100
	s_addc_u32 s57, s57, 0
	s_cmp_gt_u32 s92, 13
	s_barrier
	s_cbranch_scc0 .LBB0_740

.LBB0_903:
	s_ashr_i32 s45, s44, 31
	v_cmp_lt_i64_e32 vcc, s[0:1], v[142:143]
	s_lshl_b64 s[0:1], s[44:45], 19
	s_add_u32 s46, s42, s0
	s_addc_u32 s47, s43, s1
	s_and_b64 s[0:1], vcc, exec
	s_cselect_b32 s7, s47, s53
	s_cselect_b32 s45, s46, s52
	s_ashr_i32 s37, s36, 31
	s_lshl_b64 s[0:1], s[36:37], 19
	s_add_u32 s48, s74, s0
	s_addc_u32 s49, s75, s1
	s_and_b64 s[0:1], vcc, exec
	s_cselect_b32 s37, s49, s51
	s_cselect_b32 s67, s48, s50
	s_add_u32 s0, s52, 0x40080
	s_addc_u32 s1, s53, 0
	s_add_u32 s76, s50, 0x100
	s_addc_u32 s77, s51, 0
	s_mov_b32 s78, -2
	ds_read_b128 v[146:149], v169
	ds_read_b128 v[150:153], v169 offset:1024
	ds_read_b128 v[154:157], v169 offset:2048
	ds_read_b128 v[174:177], v169 offset:3072
	s_add_u32 s28, s0, 0xfffc0080
	s_addc_u32 s29, s1, -1
	s_cmp_eq_u32 s78, 12
	s_cselect_b32 s53, s7, s29
	s_cselect_b32 s52, s45, s28
	s_cselect_b32 s51, s37, s77
	s_cselect_b32 s50, s67, s76
	v_lshl_add_u64 v[158:159], s[0:1], 0, v[138:139]
	s_add_i32 m0, s54, 0xc000
	ds_read_b128 v[178:181], v171
	ds_read_b128 v[182:185], v171 offset:1024
	ds_read_b128 v[186:189], v171 offset:2048
	ds_read_b128 v[196:199], v171 offset:3072
	ds_read_b128 v[200:203], v171 offset:4096
	ds_read_b128 v[204:207], v171 offset:5120
	ds_read_b128 v[208:211], v171 offset:6144
	ds_read_b128 v[212:215], v171 offset:7168
	global_load_lds_dwordx4 v[158:159], off
	v_lshl_add_u64 v[158:159], s[0:1], 0, v[140:141]
	s_add_i32 m0, s54, 0xe000
	s_nop 0
	global_load_lds_dwordx4 v[158:159], off
	s_waitcnt lgkmcnt(8)
	s_barrier
	s_waitcnt lgkmcnt(0)
	v_mfma_f32_16x16x32_bf16 v[124:127], v[146:149], v[178:181], 0
	v_mfma_f32_16x16x32_bf16 v[120:123], v[154:157], v[178:181], 0
	v_mfma_f32_16x16x32_bf16 v[108:111], v[146:149], v[186:189], 0
	v_mfma_f32_16x16x32_bf16 v[104:107], v[154:157], v[186:189], 0
	v_mfma_f32_16x16x32_bf16 v[92:95], v[146:149], v[200:203], 0
	v_mfma_f32_16x16x32_bf16 v[88:91], v[154:157], v[200:203], 0
	v_mfma_f32_16x16x32_bf16 v[76:79], v[146:149], v[208:211], 0
	v_mfma_f32_16x16x32_bf16 v[72:75], v[154:157], v[208:211], 0
	v_mfma_f32_16x16x32_bf16 v[124:127], v[150:153], v[182:185], v[124:127]
	v_mfma_f32_16x16x32_bf16 v[120:123], v[174:177], v[182:185], v[120:123]
	v_mfma_f32_16x16x32_bf16 v[108:111], v[150:153], v[196:199], v[108:111]
	v_mfma_f32_16x16x32_bf16 v[104:107], v[174:177], v[196:199], v[104:107]
	v_mfma_f32_16x16x32_bf16 v[92:95], v[150:153], v[204:207], v[92:95]
	v_mfma_f32_16x16x32_bf16 v[88:91], v[174:177], v[204:207], v[88:91]
	v_mfma_f32_16x16x32_bf16 v[76:79], v[150:153], v[212:215], v[76:79]
	v_mfma_f32_16x16x32_bf16 v[72:75], v[174:177], v[212:215], v[72:75]
	s_barrier
	s_add_i32 s28, s63, s13
	v_lshl_add_u64 v[158:159], s[50:51], 0, v[132:133]
	s_mov_b32 m0, s28
	ds_read_b128 v[216:219], v172
	ds_read_b128 v[220:223], v172 offset:1024
	ds_read_b128 v[224:227], v172 offset:2048
	ds_read_b128 v[228:231], v172 offset:3072
	global_load_lds_dwordx4 v[158:159], off
	v_lshl_add_u64 v[164:165], s[50:51], 0, v[128:129]
	s_add_i32 m0, s28, 0x2000
	s_nop 0
	global_load_lds_dwordx4 v[164:165], off
	s_barrier
	s_waitcnt lgkmcnt(0)
	v_mfma_f32_16x16x32_bf16 v[116:119], v[216:219], v[178:181], 0
	v_mfma_f32_16x16x32_bf16 v[112:115], v[224:227], v[178:181], 0
	v_mfma_f32_16x16x32_bf16 v[100:103], v[216:219], v[186:189], 0
	v_mfma_f32_16x16x32_bf16 v[96:99], v[224:227], v[186:189], 0
	v_mfma_f32_16x16x32_bf16 v[84:87], v[216:219], v[200:203], 0
	v_mfma_f32_16x16x32_bf16 v[80:83], v[224:227], v[200:203], 0
	v_mfma_f32_16x16x32_bf16 v[68:71], v[216:219], v[208:211], 0
	v_mfma_f32_16x16x32_bf16 v[64:67], v[224:227], v[208:211], 0
	v_mfma_f32_16x16x32_bf16 v[116:119], v[220:223], v[182:185], v[116:119]
	v_mfma_f32_16x16x32_bf16 v[112:115], v[228:231], v[182:185], v[112:115]
	v_mfma_f32_16x16x32_bf16 v[100:103], v[220:223], v[196:199], v[100:103]
	v_mfma_f32_16x16x32_bf16 v[96:99], v[228:231], v[196:199], v[96:99]
	v_mfma_f32_16x16x32_bf16 v[84:87], v[220:223], v[204:207], v[84:87]
	v_mfma_f32_16x16x32_bf16 v[80:83], v[228:231], v[204:207], v[80:83]
	v_mfma_f32_16x16x32_bf16 v[68:71], v[220:223], v[212:215], v[68:71]
	v_mfma_f32_16x16x32_bf16 v[64:67], v[228:231], v[212:215], v[64:67]
	s_mov_b32 m0, s54
	v_lshl_add_u64 v[190:191], s[52:53], 0, v[134:135]
	s_barrier
	ds_read_b128 v[178:181], v171 offset:16384
	ds_read_b128 v[182:185], v171 offset:17408
	ds_read_b128 v[186:189], v171 offset:18432
	ds_read_b128 v[196:199], v171 offset:19456
	ds_read_b128 v[200:203], v171 offset:20480
	ds_read_b128 v[204:207], v171 offset:21504
	ds_read_b128 v[208:211], v171 offset:22528
	ds_read_b128 v[212:215], v171 offset:23552
	global_load_lds_dwordx4 v[190:191], off
	v_lshl_add_u64 v[232:233], s[52:53], 0, v[130:131]
	s_mov_b32 m0, s55
	s_nop 0
	global_load_lds_dwordx4 v[232:233], off
	s_barrier
	s_waitcnt lgkmcnt(0)
	v_mfma_f32_16x16x32_bf16 v[60:63], v[146:149], v[178:181], 0
	v_mfma_f32_16x16x32_bf16 v[56:59], v[154:157], v[178:181], 0
	v_mfma_f32_16x16x32_bf16 v[44:47], v[146:149], v[186:189], 0
	v_mfma_f32_16x16x32_bf16 v[40:43], v[154:157], v[186:189], 0
	v_mfma_f32_16x16x32_bf16 v[28:31], v[146:149], v[200:203], 0
	v_mfma_f32_16x16x32_bf16 v[24:27], v[154:157], v[200:203], 0
	v_mfma_f32_16x16x32_bf16 v[12:15], v[146:149], v[208:211], 0
	v_mfma_f32_16x16x32_bf16 v[8:11], v[154:157], v[208:211], 0
	v_mfma_f32_16x16x32_bf16 v[60:63], v[150:153], v[182:185], v[60:63]
	v_mfma_f32_16x16x32_bf16 v[56:59], v[174:177], v[182:185], v[56:59]
	v_mfma_f32_16x16x32_bf16 v[44:47], v[150:153], v[196:199], v[44:47]
	v_mfma_f32_16x16x32_bf16 v[40:43], v[174:177], v[196:199], v[40:43]
	v_mfma_f32_16x16x32_bf16 v[28:31], v[150:153], v[204:207], v[28:31]
	v_mfma_f32_16x16x32_bf16 v[24:27], v[174:177], v[204:207], v[24:27]
	v_mfma_f32_16x16x32_bf16 v[12:15], v[150:153], v[212:215], v[12:15]
	v_mfma_f32_16x16x32_bf16 v[8:11], v[174:177], v[212:215], v[8:11]
	s_barrier
	s_add_u32 s80, s50, 0x10000
	s_addc_u32 s81, s51, 0
	s_add_i32 s28, s64, s13
	v_lshl_add_u64 v[146:147], s[80:81], 0, v[132:133]
	s_mov_b32 m0, s28
	s_nop 0
	global_load_lds_dwordx4 v[146:147], off
	v_lshl_add_u64 v[146:147], s[80:81], 0, v[128:129]
	s_add_i32 m0, s28, 0x2000
	s_nop 0
	global_load_lds_dwordx4 v[146:147], off
	s_waitcnt vmcnt(6)
	s_barrier
	v_mfma_f32_16x16x32_bf16 v[52:55], v[216:219], v[178:181], 0
	v_mfma_f32_16x16x32_bf16 v[48:51], v[224:227], v[178:181], 0
	v_mfma_f32_16x16x32_bf16 v[36:39], v[216:219], v[186:189], 0
	v_mfma_f32_16x16x32_bf16 v[32:35], v[224:227], v[186:189], 0
	v_mfma_f32_16x16x32_bf16 v[20:23], v[216:219], v[200:203], 0
	v_mfma_f32_16x16x32_bf16 v[16:19], v[224:227], v[200:203], 0
	v_mfma_f32_16x16x32_bf16 v[4:7], v[216:219], v[208:211], 0
	v_mfma_f32_16x16x32_bf16 v[0:3], v[224:227], v[208:211], 0
	v_mfma_f32_16x16x32_bf16 v[52:55], v[220:223], v[182:185], v[52:55]
	v_mfma_f32_16x16x32_bf16 v[48:51], v[228:231], v[182:185], v[48:51]
	v_mfma_f32_16x16x32_bf16 v[36:39], v[220:223], v[196:199], v[36:39]
	v_mfma_f32_16x16x32_bf16 v[32:35], v[228:231], v[196:199], v[32:35]
	v_mfma_f32_16x16x32_bf16 v[20:23], v[220:223], v[204:207], v[20:23]
	v_mfma_f32_16x16x32_bf16 v[16:19], v[228:231], v[204:207], v[16:19]
	v_mfma_f32_16x16x32_bf16 v[4:7], v[220:223], v[212:215], v[4:7]
	v_mfma_f32_16x16x32_bf16 v[0:3], v[228:231], v[212:215], v[0:3]
	s_add_i32 s28, 0, 0x18000
	v_add_u32_e32 v160, s28, v163
	s_barrier
	ds_read_b128 v[146:149], v160
	ds_read_b128 v[150:153], v160 offset:1024
	ds_read_b128 v[154:157], v160 offset:2048
	ds_read_b128 v[174:177], v160 offset:3072
	s_add_u32 s52, s52, 0x40000
	s_addc_u32 s53, s53, 0
	s_mov_b32 m0, s56
	v_lshl_add_u64 v[216:217], s[52:53], 0, v[134:135]
	ds_read_b128 v[178:181], v171 offset:32768
	ds_read_b128 v[182:185], v171 offset:33792
	ds_read_b128 v[186:189], v171 offset:34816
	ds_read_b128 v[196:199], v171 offset:35840
	ds_read_b128 v[200:203], v171 offset:36864
	ds_read_b128 v[204:207], v171 offset:37888
	ds_read_b128 v[208:211], v171 offset:38912
	ds_read_b128 v[212:215], v171 offset:39936
	global_load_lds_dwordx4 v[216:217], off
	v_lshl_add_u64 v[216:217], s[52:53], 0, v[130:131]
	s_mov_b32 m0, s57
	s_nop 0
	global_load_lds_dwordx4 v[216:217], off
	s_waitcnt lgkmcnt(8)
	s_barrier
	s_waitcnt lgkmcnt(0)
	v_mfma_f32_16x16x32_bf16 v[124:127], v[146:149], v[178:181], v[124:127]
	v_mfma_f32_16x16x32_bf16 v[120:123], v[154:157], v[178:181], v[120:123]
	v_mfma_f32_16x16x32_bf16 v[108:111], v[146:149], v[186:189], v[108:111]
	v_mfma_f32_16x16x32_bf16 v[104:107], v[154:157], v[186:189], v[104:107]
	v_mfma_f32_16x16x32_bf16 v[92:95], v[146:149], v[200:203], v[92:95]
	v_mfma_f32_16x16x32_bf16 v[88:91], v[154:157], v[200:203], v[88:91]
	v_mfma_f32_16x16x32_bf16 v[76:79], v[146:149], v[208:211], v[76:79]
	v_mfma_f32_16x16x32_bf16 v[72:75], v[154:157], v[208:211], v[72:75]
	v_mfma_f32_16x16x32_bf16 v[124:127], v[150:153], v[182:185], v[124:127]
	v_mfma_f32_16x16x32_bf16 v[120:123], v[174:177], v[182:185], v[120:123]
	v_mfma_f32_16x16x32_bf16 v[108:111], v[150:153], v[196:199], v[108:111]
	v_mfma_f32_16x16x32_bf16 v[104:107], v[174:177], v[196:199], v[104:107]
	v_mfma_f32_16x16x32_bf16 v[92:95], v[150:153], v[204:207], v[92:95]
	v_mfma_f32_16x16x32_bf16 v[88:91], v[174:177], v[204:207], v[88:91]
	v_mfma_f32_16x16x32_bf16 v[76:79], v[150:153], v[212:215], v[76:79]
	v_mfma_f32_16x16x32_bf16 v[72:75], v[174:177], v[212:215], v[72:75]
	s_barrier
	s_add_i32 s29, 0, 0x1c000
	s_add_i32 s28, s28, s13
	v_add_u32_e32 v160, s29, v163
	v_lshl_add_u64 v[158:159], v[158:159], 0, s[8:9]
	s_mov_b32 m0, s28
	ds_read_b128 v[216:219], v160
	ds_read_b128 v[220:223], v160 offset:1024
	ds_read_b128 v[224:227], v160 offset:2048
	ds_read_b128 v[228:231], v160 offset:3072
	global_load_lds_dwordx4 v[158:159], off
	v_lshl_add_u64 v[158:159], v[164:165], 0, s[8:9]
	s_add_i32 m0, s28, 0x2000
	s_nop 0
	global_load_lds_dwordx4 v[158:159], off
	s_barrier
	s_waitcnt lgkmcnt(0)
	v_mfma_f32_16x16x32_bf16 v[116:119], v[216:219], v[178:181], v[116:119]
	v_mfma_f32_16x16x32_bf16 v[112:115], v[224:227], v[178:181], v[112:115]
	v_mfma_f32_16x16x32_bf16 v[100:103], v[216:219], v[186:189], v[100:103]
	v_mfma_f32_16x16x32_bf16 v[96:99], v[224:227], v[186:189], v[96:99]
	v_mfma_f32_16x16x32_bf16 v[84:87], v[216:219], v[200:203], v[84:87]
	v_mfma_f32_16x16x32_bf16 v[80:83], v[224:227], v[200:203], v[80:83]
	v_mfma_f32_16x16x32_bf16 v[68:71], v[216:219], v[208:211], v[68:71]
	v_mfma_f32_16x16x32_bf16 v[64:67], v[224:227], v[208:211], v[64:67]
	v_mfma_f32_16x16x32_bf16 v[116:119], v[220:223], v[182:185], v[116:119]
	v_mfma_f32_16x16x32_bf16 v[112:115], v[228:231], v[182:185], v[112:115]
	v_mfma_f32_16x16x32_bf16 v[100:103], v[220:223], v[196:199], v[100:103]
	v_mfma_f32_16x16x32_bf16 v[96:99], v[228:231], v[196:199], v[96:99]
	v_mfma_f32_16x16x32_bf16 v[84:87], v[220:223], v[204:207], v[84:87]
	v_mfma_f32_16x16x32_bf16 v[80:83], v[228:231], v[204:207], v[80:83]
	v_mfma_f32_16x16x32_bf16 v[68:71], v[220:223], v[212:215], v[68:71]
	v_mfma_f32_16x16x32_bf16 v[64:67], v[228:231], v[212:215], v[64:67]
	s_mov_b32 m0, s60
	v_lshl_add_u64 v[158:159], v[190:191], 0, s[8:9]
	s_barrier
	ds_read_b128 v[178:181], v171 offset:49152
	ds_read_b128 v[182:185], v171 offset:50176
	ds_read_b128 v[186:189], v171 offset:51200
	ds_read_b128 v[196:199], v171 offset:52224
	ds_read_b128 v[200:203], v171 offset:53248
	ds_read_b128 v[204:207], v171 offset:54272
	ds_read_b128 v[208:211], v171 offset:55296
	ds_read_b128 v[212:215], v171 offset:56320
	global_load_lds_dwordx4 v[158:159], off
	v_lshl_add_u64 v[158:159], v[232:233], 0, s[8:9]
	s_mov_b32 m0, s61
	s_nop 0
	global_load_lds_dwordx4 v[158:159], off
	s_barrier
	s_waitcnt lgkmcnt(0)
	v_mfma_f32_16x16x32_bf16 v[60:63], v[146:149], v[178:181], v[60:63]
	v_mfma_f32_16x16x32_bf16 v[56:59], v[154:157], v[178:181], v[56:59]
	v_mfma_f32_16x16x32_bf16 v[44:47], v[146:149], v[186:189], v[44:47]
	v_mfma_f32_16x16x32_bf16 v[40:43], v[154:157], v[186:189], v[40:43]
	v_mfma_f32_16x16x32_bf16 v[28:31], v[146:149], v[200:203], v[28:31]
	v_mfma_f32_16x16x32_bf16 v[24:27], v[154:157], v[200:203], v[24:27]
	v_mfma_f32_16x16x32_bf16 v[12:15], v[146:149], v[208:211], v[12:15]
	v_mfma_f32_16x16x32_bf16 v[8:11], v[154:157], v[208:211], v[8:11]
	v_mfma_f32_16x16x32_bf16 v[60:63], v[150:153], v[182:185], v[60:63]
	v_mfma_f32_16x16x32_bf16 v[56:59], v[174:177], v[182:185], v[56:59]
	v_mfma_f32_16x16x32_bf16 v[44:47], v[150:153], v[196:199], v[44:47]
	v_mfma_f32_16x16x32_bf16 v[40:43], v[174:177], v[196:199], v[40:43]
	v_mfma_f32_16x16x32_bf16 v[28:31], v[150:153], v[204:207], v[28:31]
	v_mfma_f32_16x16x32_bf16 v[24:27], v[174:177], v[204:207], v[24:27]
	v_mfma_f32_16x16x32_bf16 v[12:15], v[150:153], v[212:215], v[12:15]
	v_mfma_f32_16x16x32_bf16 v[8:11], v[174:177], v[212:215], v[8:11]
	s_barrier
	s_add_u32 s50, s50, 0x10080
	s_addc_u32 s51, s51, 0
	s_add_i32 s28, s29, s13
	v_lshl_add_u64 v[146:147], s[50:51], 0, v[132:133]
	s_mov_b32 m0, s28
	s_nop 0
	global_load_lds_dwordx4 v[146:147], off
	v_lshl_add_u64 v[146:147], s[50:51], 0, v[128:129]
	s_add_i32 m0, s28, 0x2000
	s_nop 0
	global_load_lds_dwordx4 v[146:147], off
	s_waitcnt vmcnt(6)
	s_barrier
	v_mfma_f32_16x16x32_bf16 v[52:55], v[216:219], v[178:181], v[52:55]
	v_mfma_f32_16x16x32_bf16 v[48:51], v[224:227], v[178:181], v[48:51]
	v_mfma_f32_16x16x32_bf16 v[36:39], v[216:219], v[186:189], v[36:39]
	v_mfma_f32_16x16x32_bf16 v[32:35], v[224:227], v[186:189], v[32:35]
	v_mfma_f32_16x16x32_bf16 v[20:23], v[216:219], v[200:203], v[20:23]
	v_mfma_f32_16x16x32_bf16 v[16:19], v[224:227], v[200:203], v[16:19]
	v_mfma_f32_16x16x32_bf16 v[4:7], v[216:219], v[208:211], v[4:7]
	v_mfma_f32_16x16x32_bf16 v[0:3], v[224:227], v[208:211], v[0:3]
	v_mfma_f32_16x16x32_bf16 v[52:55], v[220:223], v[182:185], v[52:55]
	v_mfma_f32_16x16x32_bf16 v[48:51], v[228:231], v[182:185], v[48:51]
	v_mfma_f32_16x16x32_bf16 v[36:39], v[220:223], v[196:199], v[36:39]
	v_mfma_f32_16x16x32_bf16 v[32:35], v[228:231], v[196:199], v[32:35]
	v_mfma_f32_16x16x32_bf16 v[20:23], v[220:223], v[204:207], v[20:23]
	v_mfma_f32_16x16x32_bf16 v[16:19], v[228:231], v[204:207], v[16:19]
	v_mfma_f32_16x16x32_bf16 v[4:7], v[220:223], v[212:215], v[4:7]
	v_mfma_f32_16x16x32_bf16 v[0:3], v[228:231], v[212:215], v[0:3]
	s_add_i32 s78, s78, 2
	s_add_u32 s0, s0, 0x100
	s_addc_u32 s1, s1, 0
	s_add_u32 s76, s76, 0x100
	s_addc_u32 s77, s77, 0
	s_cmp_gt_u32 s78, 13
	s_barrier
	s_cbranch_scc0 .LBB0_904

.LBB0_996:
	s_ashr_i32 s41, s40, 31
	v_cmp_lt_i64_e32 vcc, s[44:45], v[148:149]
	s_lshl_b64 s[44:45], s[40:41], 18
	s_add_u32 s44, s74, s44
	s_addc_u32 s45, s75, s45
	s_and_b64 s[46:47], vcc, exec
	s_cselect_b32 s9, s45, s49
	s_cselect_b32 s41, s44, s48
	s_ashr_i32 s39, s38, 31
	s_lshl_b64 s[46:47], s[38:39], 18
	s_add_u32 s46, s72, s46
	s_addc_u32 s47, s73, s47
	s_and_b64 s[52:53], vcc, exec
	s_cselect_b32 s39, s47, s51
	s_cselect_b32 s76, s46, s50
	s_add_u32 s48, s48, 0x20080
	s_addc_u32 s49, s49, 0
	s_add_u32 s77, s50, 0x100
	s_addc_u32 s78, s51, 0
	s_mov_b32 s79, -2
	s_waitcnt lgkmcnt(0)
	ds_read_b128 v[128:131], v164
	ds_read_b128 v[132:135], v164 offset:1024
	ds_read_b128 v[152:155], v164 offset:2048
	ds_read_b128 v[156:159], v164 offset:3072
	s_add_u32 s28, s48, 0xfffe0080
	s_addc_u32 s29, s49, -1
	s_cmp_eq_u32 s79, 4
	s_cselect_b32 s53, s9, s29
	s_cselect_b32 s52, s41, s28
	s_cselect_b32 s51, s39, s78
	s_cselect_b32 s50, s76, s77
	v_lshl_add_u64 v[204:205], s[48:49], 0, v[144:145]
	s_add_i32 m0, s55, 0xc000
	ds_read_b128 v[168:171], v165
	ds_read_b128 v[172:175], v165 offset:1024
	ds_read_b128 v[176:179], v165 offset:2048
	ds_read_b128 v[180:183], v165 offset:3072
	ds_read_b128 v[184:187], v165 offset:4096
	ds_read_b128 v[188:191], v165 offset:5120
	ds_read_b128 v[196:199], v165 offset:6144
	ds_read_b128 v[200:203], v165 offset:7168
	global_load_lds_dwordx4 v[204:205], off
	v_lshl_add_u64 v[204:205], s[48:49], 0, v[146:147]
	s_add_i32 m0, s55, 0xe000
	s_nop 0
	global_load_lds_dwordx4 v[204:205], off
	s_waitcnt lgkmcnt(8)
	s_barrier
	s_waitcnt lgkmcnt(0)
	v_mfma_f32_16x16x32_bf16 v[124:127], v[128:131], v[168:171], 0
	v_mfma_f32_16x16x32_bf16 v[120:123], v[152:155], v[168:171], 0
	v_mfma_f32_16x16x32_bf16 v[108:111], v[128:131], v[176:179], 0
	v_mfma_f32_16x16x32_bf16 v[104:107], v[152:155], v[176:179], 0
	v_mfma_f32_16x16x32_bf16 v[92:95], v[128:131], v[184:187], 0
	v_mfma_f32_16x16x32_bf16 v[88:91], v[152:155], v[184:187], 0
	v_mfma_f32_16x16x32_bf16 v[76:79], v[128:131], v[196:199], 0
	v_mfma_f32_16x16x32_bf16 v[72:75], v[152:155], v[196:199], 0
	v_mfma_f32_16x16x32_bf16 v[124:127], v[132:135], v[172:175], v[124:127]
	v_mfma_f32_16x16x32_bf16 v[120:123], v[156:159], v[172:175], v[120:123]
	v_mfma_f32_16x16x32_bf16 v[108:111], v[132:135], v[180:183], v[108:111]
	v_mfma_f32_16x16x32_bf16 v[104:107], v[156:159], v[180:183], v[104:107]
	v_mfma_f32_16x16x32_bf16 v[92:95], v[132:135], v[188:191], v[92:95]
	v_mfma_f32_16x16x32_bf16 v[88:91], v[156:159], v[188:191], v[88:91]
	v_mfma_f32_16x16x32_bf16 v[76:79], v[132:135], v[200:203], v[76:79]
	v_mfma_f32_16x16x32_bf16 v[72:75], v[156:159], v[200:203], v[72:75]
	s_barrier
	s_add_i32 s28, s65, s54
	v_lshl_add_u64 v[220:221], s[50:51], 0, v[138:139]
	s_mov_b32 m0, s28
	ds_read_b128 v[204:207], v166
	ds_read_b128 v[208:211], v166 offset:1024
	ds_read_b128 v[212:215], v166 offset:2048
	ds_read_b128 v[216:219], v166 offset:3072
	global_load_lds_dwordx4 v[220:221], off
	v_lshl_add_u64 v[222:223], s[50:51], 0, v[142:143]
	s_add_i32 m0, s28, 0x2000
	s_nop 0
	global_load_lds_dwordx4 v[222:223], off
	s_barrier
	s_waitcnt lgkmcnt(0)
	v_mfma_f32_16x16x32_bf16 v[116:119], v[204:207], v[168:171], 0
	v_mfma_f32_16x16x32_bf16 v[112:115], v[212:215], v[168:171], 0
	v_mfma_f32_16x16x32_bf16 v[100:103], v[204:207], v[176:179], 0
	v_mfma_f32_16x16x32_bf16 v[96:99], v[212:215], v[176:179], 0
	v_mfma_f32_16x16x32_bf16 v[84:87], v[204:207], v[184:187], 0
	v_mfma_f32_16x16x32_bf16 v[80:83], v[212:215], v[184:187], 0
	v_mfma_f32_16x16x32_bf16 v[68:71], v[204:207], v[196:199], 0
	v_mfma_f32_16x16x32_bf16 v[64:67], v[212:215], v[196:199], 0
	v_mfma_f32_16x16x32_bf16 v[116:119], v[208:211], v[172:175], v[116:119]
	v_mfma_f32_16x16x32_bf16 v[112:115], v[216:219], v[172:175], v[112:115]
	v_mfma_f32_16x16x32_bf16 v[100:103], v[208:211], v[180:183], v[100:103]
	v_mfma_f32_16x16x32_bf16 v[96:99], v[216:219], v[180:183], v[96:99]
	v_mfma_f32_16x16x32_bf16 v[84:87], v[208:211], v[188:191], v[84:87]
	v_mfma_f32_16x16x32_bf16 v[80:83], v[216:219], v[188:191], v[80:83]
	v_mfma_f32_16x16x32_bf16 v[68:71], v[208:211], v[200:203], v[68:71]
	v_mfma_f32_16x16x32_bf16 v[64:67], v[216:219], v[200:203], v[64:67]
	s_mov_b32 m0, s55
	v_lshl_add_u64 v[224:225], s[52:53], 0, v[136:137]
	s_barrier
	ds_read_b128 v[168:171], v165 offset:16384
	ds_read_b128 v[172:175], v165 offset:17408
	ds_read_b128 v[176:179], v165 offset:18432
	ds_read_b128 v[180:183], v165 offset:19456
	ds_read_b128 v[184:187], v165 offset:20480
	ds_read_b128 v[188:191], v165 offset:21504
	ds_read_b128 v[196:199], v165 offset:22528
	ds_read_b128 v[200:203], v165 offset:23552
	global_load_lds_dwordx4 v[224:225], off
	v_lshl_add_u64 v[226:227], s[52:53], 0, v[140:141]
	s_mov_b32 m0, s56
	s_nop 0
	global_load_lds_dwordx4 v[226:227], off
	s_barrier
	s_waitcnt lgkmcnt(0)
	v_mfma_f32_16x16x32_bf16 v[60:63], v[128:131], v[168:171], 0
	v_mfma_f32_16x16x32_bf16 v[56:59], v[152:155], v[168:171], 0
	v_mfma_f32_16x16x32_bf16 v[44:47], v[128:131], v[176:179], 0
	v_mfma_f32_16x16x32_bf16 v[40:43], v[152:155], v[176:179], 0
	v_mfma_f32_16x16x32_bf16 v[28:31], v[128:131], v[184:187], 0
	v_mfma_f32_16x16x32_bf16 v[24:27], v[152:155], v[184:187], 0
	v_mfma_f32_16x16x32_bf16 v[12:15], v[128:131], v[196:199], 0
	v_mfma_f32_16x16x32_bf16 v[8:11], v[152:155], v[196:199], 0
	v_mfma_f32_16x16x32_bf16 v[60:63], v[132:135], v[172:175], v[60:63]
	v_mfma_f32_16x16x32_bf16 v[56:59], v[156:159], v[172:175], v[56:59]
	v_mfma_f32_16x16x32_bf16 v[44:47], v[132:135], v[180:183], v[44:47]
	v_mfma_f32_16x16x32_bf16 v[40:43], v[156:159], v[180:183], v[40:43]
	v_mfma_f32_16x16x32_bf16 v[28:31], v[132:135], v[188:191], v[28:31]
	v_mfma_f32_16x16x32_bf16 v[24:27], v[156:159], v[188:191], v[24:27]
	v_mfma_f32_16x16x32_bf16 v[12:15], v[132:135], v[200:203], v[12:15]
	v_mfma_f32_16x16x32_bf16 v[8:11], v[156:159], v[200:203], v[8:11]
	s_barrier
	s_add_u32 s80, s50, 0x8000
	s_addc_u32 s81, s51, 0
	s_add_i32 s28, s66, s54
	v_lshl_add_u64 v[128:129], s[80:81], 0, v[138:139]
	s_mov_b32 m0, s28
	s_nop 0
	global_load_lds_dwordx4 v[128:129], off
	v_lshl_add_u64 v[128:129], s[80:81], 0, v[142:143]
	s_add_i32 m0, s28, 0x2000
	s_nop 0
	global_load_lds_dwordx4 v[128:129], off
	s_waitcnt vmcnt(6)
	s_barrier
	v_mfma_f32_16x16x32_bf16 v[52:55], v[204:207], v[168:171], 0
	v_mfma_f32_16x16x32_bf16 v[48:51], v[212:215], v[168:171], 0
	v_mfma_f32_16x16x32_bf16 v[36:39], v[204:207], v[176:179], 0
	v_mfma_f32_16x16x32_bf16 v[32:35], v[212:215], v[176:179], 0
	v_mfma_f32_16x16x32_bf16 v[20:23], v[204:207], v[184:187], 0
	v_mfma_f32_16x16x32_bf16 v[16:19], v[212:215], v[184:187], 0
	v_mfma_f32_16x16x32_bf16 v[4:7], v[204:207], v[196:199], 0
	v_mfma_f32_16x16x32_bf16 v[0:3], v[212:215], v[196:199], 0
	v_mfma_f32_16x16x32_bf16 v[52:55], v[208:211], v[172:175], v[52:55]
	v_mfma_f32_16x16x32_bf16 v[48:51], v[216:219], v[172:175], v[48:51]
	v_mfma_f32_16x16x32_bf16 v[36:39], v[208:211], v[180:183], v[36:39]
	v_mfma_f32_16x16x32_bf16 v[32:35], v[216:219], v[180:183], v[32:35]
	v_mfma_f32_16x16x32_bf16 v[20:23], v[208:211], v[188:191], v[20:23]
	v_mfma_f32_16x16x32_bf16 v[16:19], v[216:219], v[188:191], v[16:19]
	v_mfma_f32_16x16x32_bf16 v[4:7], v[208:211], v[200:203], v[4:7]
	v_mfma_f32_16x16x32_bf16 v[0:3], v[216:219], v[200:203], v[0:3]
	s_add_i32 s28, 0, 0x18000
	v_add_u32_e32 v156, s28, v161
	s_barrier
	ds_read_b128 v[128:131], v156
	ds_read_b128 v[132:135], v156 offset:1024
	ds_read_b128 v[152:155], v156 offset:2048
	ds_read_b128 v[156:159], v156 offset:3072
	s_add_u32 s52, s52, 0x20000
	s_addc_u32 s53, s53, 0
	s_mov_b32 m0, s57
	v_lshl_add_u64 v[204:205], s[52:53], 0, v[136:137]
	ds_read_b128 v[168:171], v165 offset:32768
	ds_read_b128 v[172:175], v165 offset:33792
	ds_read_b128 v[176:179], v165 offset:34816
	ds_read_b128 v[180:183], v165 offset:35840
	ds_read_b128 v[184:187], v165 offset:36864
	ds_read_b128 v[188:191], v165 offset:37888
	ds_read_b128 v[196:199], v165 offset:38912
	ds_read_b128 v[200:203], v165 offset:39936
	global_load_lds_dwordx4 v[204:205], off
	v_lshl_add_u64 v[204:205], s[52:53], 0, v[140:141]
	s_mov_b32 m0, s58
	s_nop 0
	global_load_lds_dwordx4 v[204:205], off
	s_waitcnt lgkmcnt(8)
	s_barrier
	s_waitcnt lgkmcnt(0)
	v_mfma_f32_16x16x32_bf16 v[124:127], v[128:131], v[168:171], v[124:127]
	v_mfma_f32_16x16x32_bf16 v[120:123], v[152:155], v[168:171], v[120:123]
	v_mfma_f32_16x16x32_bf16 v[108:111], v[128:131], v[176:179], v[108:111]
	v_mfma_f32_16x16x32_bf16 v[104:107], v[152:155], v[176:179], v[104:107]
	v_mfma_f32_16x16x32_bf16 v[92:95], v[128:131], v[184:187], v[92:95]
	v_mfma_f32_16x16x32_bf16 v[88:91], v[152:155], v[184:187], v[88:91]
	v_mfma_f32_16x16x32_bf16 v[76:79], v[128:131], v[196:199], v[76:79]
	v_mfma_f32_16x16x32_bf16 v[72:75], v[152:155], v[196:199], v[72:75]
	v_mfma_f32_16x16x32_bf16 v[124:127], v[132:135], v[172:175], v[124:127]
	v_mfma_f32_16x16x32_bf16 v[120:123], v[156:159], v[172:175], v[120:123]
	v_mfma_f32_16x16x32_bf16 v[108:111], v[132:135], v[180:183], v[108:111]
	v_mfma_f32_16x16x32_bf16 v[104:107], v[156:159], v[180:183], v[104:107]
	v_mfma_f32_16x16x32_bf16 v[92:95], v[132:135], v[188:191], v[92:95]
	v_mfma_f32_16x16x32_bf16 v[88:91], v[156:159], v[188:191], v[88:91]
	v_mfma_f32_16x16x32_bf16 v[76:79], v[132:135], v[200:203], v[76:79]
	v_mfma_f32_16x16x32_bf16 v[72:75], v[156:159], v[200:203], v[72:75]
	s_barrier
	s_add_i32 s29, 0, 0x1c000
	s_add_i32 s28, s28, s54
	v_add_u32_e32 v195, s29, v161
	v_lshl_add_u64 v[220:221], v[220:221], 0, s[36:37]
	s_mov_b32 m0, s28
	ds_read_b128 v[204:207], v195
	ds_read_b128 v[208:211], v195 offset:1024
	ds_read_b128 v[212:215], v195 offset:2048
	ds_read_b128 v[216:219], v195 offset:3072
	global_load_lds_dwordx4 v[220:221], off
	v_lshl_add_u64 v[220:221], v[222:223], 0, s[36:37]
	s_add_i32 m0, s28, 0x2000
	s_nop 0
	global_load_lds_dwordx4 v[220:221], off
	s_barrier
	s_waitcnt lgkmcnt(0)
	v_mfma_f32_16x16x32_bf16 v[116:119], v[204:207], v[168:171], v[116:119]
	v_mfma_f32_16x16x32_bf16 v[112:115], v[212:215], v[168:171], v[112:115]
	v_mfma_f32_16x16x32_bf16 v[100:103], v[204:207], v[176:179], v[100:103]
	v_mfma_f32_16x16x32_bf16 v[96:99], v[212:215], v[176:179], v[96:99]
	v_mfma_f32_16x16x32_bf16 v[84:87], v[204:207], v[184:187], v[84:87]
	v_mfma_f32_16x16x32_bf16 v[80:83], v[212:215], v[184:187], v[80:83]
	v_mfma_f32_16x16x32_bf16 v[68:71], v[204:207], v[196:199], v[68:71]
	v_mfma_f32_16x16x32_bf16 v[64:67], v[212:215], v[196:199], v[64:67]
	v_mfma_f32_16x16x32_bf16 v[116:119], v[208:211], v[172:175], v[116:119]
	v_mfma_f32_16x16x32_bf16 v[112:115], v[216:219], v[172:175], v[112:115]
	v_mfma_f32_16x16x32_bf16 v[100:103], v[208:211], v[180:183], v[100:103]
	v_mfma_f32_16x16x32_bf16 v[96:99], v[216:219], v[180:183], v[96:99]
	v_mfma_f32_16x16x32_bf16 v[84:87], v[208:211], v[188:191], v[84:87]
	v_mfma_f32_16x16x32_bf16 v[80:83], v[216:219], v[188:191], v[80:83]
	v_mfma_f32_16x16x32_bf16 v[68:71], v[208:211], v[200:203], v[68:71]
	v_mfma_f32_16x16x32_bf16 v[64:67], v[216:219], v[200:203], v[64:67]
	s_mov_b32 m0, s62
	v_lshl_add_u64 v[220:221], v[224:225], 0, s[36:37]
	s_barrier
	ds_read_b128 v[168:171], v165 offset:49152
	ds_read_b128 v[172:175], v165 offset:50176
	ds_read_b128 v[176:179], v165 offset:51200
	ds_read_b128 v[180:183], v165 offset:52224
	ds_read_b128 v[184:187], v165 offset:53248
	ds_read_b128 v[188:191], v165 offset:54272
	ds_read_b128 v[196:199], v165 offset:55296
	ds_read_b128 v[200:203], v165 offset:56320
	global_load_lds_dwordx4 v[220:221], off
	v_lshl_add_u64 v[220:221], v[226:227], 0, s[36:37]
	s_mov_b32 m0, s63
	s_nop 0
	global_load_lds_dwordx4 v[220:221], off
	s_barrier
	s_waitcnt lgkmcnt(0)
	v_mfma_f32_16x16x32_bf16 v[60:63], v[128:131], v[168:171], v[60:63]
	v_mfma_f32_16x16x32_bf16 v[56:59], v[152:155], v[168:171], v[56:59]
	v_mfma_f32_16x16x32_bf16 v[44:47], v[128:131], v[176:179], v[44:47]
	v_mfma_f32_16x16x32_bf16 v[40:43], v[152:155], v[176:179], v[40:43]
	v_mfma_f32_16x16x32_bf16 v[28:31], v[128:131], v[184:187], v[28:31]
	v_mfma_f32_16x16x32_bf16 v[24:27], v[152:155], v[184:187], v[24:27]
	v_mfma_f32_16x16x32_bf16 v[12:15], v[128:131], v[196:199], v[12:15]
	v_mfma_f32_16x16x32_bf16 v[8:11], v[152:155], v[196:199], v[8:11]
	v_mfma_f32_16x16x32_bf16 v[60:63], v[132:135], v[172:175], v[60:63]
	v_mfma_f32_16x16x32_bf16 v[56:59], v[156:159], v[172:175], v[56:59]
	v_mfma_f32_16x16x32_bf16 v[44:47], v[132:135], v[180:183], v[44:47]
	v_mfma_f32_16x16x32_bf16 v[40:43], v[156:159], v[180:183], v[40:43]
	v_mfma_f32_16x16x32_bf16 v[28:31], v[132:135], v[188:191], v[28:31]
	v_mfma_f32_16x16x32_bf16 v[24:27], v[156:159], v[188:191], v[24:27]
	v_mfma_f32_16x16x32_bf16 v[12:15], v[132:135], v[200:203], v[12:15]
	v_mfma_f32_16x16x32_bf16 v[8:11], v[156:159], v[200:203], v[8:11]
	s_barrier
	s_add_u32 s50, s50, 0x8080
	s_addc_u32 s51, s51, 0
	s_add_i32 s28, s29, s54
	v_lshl_add_u64 v[128:129], s[50:51], 0, v[138:139]
	s_mov_b32 m0, s28
	s_nop 0
	global_load_lds_dwordx4 v[128:129], off
	v_lshl_add_u64 v[128:129], s[50:51], 0, v[142:143]
	s_add_i32 m0, s28, 0x2000
	s_nop 0
	global_load_lds_dwordx4 v[128:129], off
	s_waitcnt vmcnt(6)
	s_barrier
	v_mfma_f32_16x16x32_bf16 v[52:55], v[204:207], v[168:171], v[52:55]
	v_mfma_f32_16x16x32_bf16 v[48:51], v[212:215], v[168:171], v[48:51]
	v_mfma_f32_16x16x32_bf16 v[36:39], v[204:207], v[176:179], v[36:39]
	v_mfma_f32_16x16x32_bf16 v[32:35], v[212:215], v[176:179], v[32:35]
	v_mfma_f32_16x16x32_bf16 v[20:23], v[204:207], v[184:187], v[20:23]
	v_mfma_f32_16x16x32_bf16 v[16:19], v[212:215], v[184:187], v[16:19]
	v_mfma_f32_16x16x32_bf16 v[4:7], v[204:207], v[196:199], v[4:7]
	v_mfma_f32_16x16x32_bf16 v[0:3], v[212:215], v[196:199], v[0:3]
	v_mfma_f32_16x16x32_bf16 v[52:55], v[208:211], v[172:175], v[52:55]
	v_mfma_f32_16x16x32_bf16 v[48:51], v[216:219], v[172:175], v[48:51]
	v_mfma_f32_16x16x32_bf16 v[36:39], v[208:211], v[180:183], v[36:39]
	v_mfma_f32_16x16x32_bf16 v[32:35], v[216:219], v[180:183], v[32:35]
	v_mfma_f32_16x16x32_bf16 v[20:23], v[208:211], v[188:191], v[20:23]
	v_mfma_f32_16x16x32_bf16 v[16:19], v[216:219], v[188:191], v[16:19]
	v_mfma_f32_16x16x32_bf16 v[4:7], v[208:211], v[200:203], v[4:7]
	v_mfma_f32_16x16x32_bf16 v[0:3], v[216:219], v[200:203], v[0:3]
	s_add_i32 s79, s79, 2
	s_add_u32 s48, s48, 0x100
	s_addc_u32 s49, s49, 0
	s_add_u32 s77, s77, 0x100
	s_addc_u32 s78, s78, 0
	s_cmp_gt_u32 s79, 5
	s_barrier
	s_cbranch_scc0 .LBB0_997

.LBB0_1168:
	s_add_u32 s63, s42, 0x100
	s_addc_u32 s64, s43, 0
	s_mov_b32 s65, -2
	s_waitcnt lgkmcnt(0)
	ds_read_b128 v[128:131], v167
	ds_read_b128 v[132:135], v167 offset:1024
	ds_read_b128 v[136:139], v167 offset:2048
	ds_read_b128 v[156:159], v167 offset:3072
	s_add_u32 s6, s40, 0x100
	s_addc_u32 s7, s41, 0
	s_cmp_eq_u32 s65, 40
	s_cselect_b32 s45, s1, s7
	s_cselect_b32 s44, s0, s6
	s_cselect_b32 s43, s39, s64
	s_cselect_b32 s42, s38, s63
	v_lshl_add_u64 v[202:203], s[40:41], 0, v[148:149]
	s_add_i32 m0, s47, 0xc000
	ds_read_b128 v[160:163], v168
	ds_read_b128 v[172:175], v168 offset:1024
	ds_read_b128 v[176:179], v168 offset:2048
	ds_read_b128 v[180:183], v168 offset:3072
	ds_read_b128 v[184:187], v168 offset:4096
	ds_read_b128 v[188:191], v168 offset:5120
	ds_read_b128 v[194:197], v168 offset:6144
	ds_read_b128 v[198:201], v168 offset:7168
	global_load_lds_dwordx4 v[202:203], off
	v_lshl_add_u64 v[202:203], s[40:41], 0, v[150:151]
	s_add_i32 m0, s47, 0xe000
	s_nop 0
	global_load_lds_dwordx4 v[202:203], off
	s_waitcnt lgkmcnt(8)
	s_barrier
	s_waitcnt lgkmcnt(0)
	v_mfma_f32_16x16x32_bf16 v[124:127], v[128:131], v[160:163], 0
	v_mfma_f32_16x16x32_bf16 v[120:123], v[136:139], v[160:163], 0
	v_mfma_f32_16x16x32_bf16 v[108:111], v[128:131], v[176:179], 0
	v_mfma_f32_16x16x32_bf16 v[104:107], v[136:139], v[176:179], 0
	v_mfma_f32_16x16x32_bf16 v[92:95], v[128:131], v[184:187], 0
	v_mfma_f32_16x16x32_bf16 v[88:91], v[136:139], v[184:187], 0
	v_mfma_f32_16x16x32_bf16 v[76:79], v[128:131], v[194:197], 0
	v_mfma_f32_16x16x32_bf16 v[72:75], v[136:139], v[194:197], 0
	v_mfma_f32_16x16x32_bf16 v[124:127], v[132:135], v[172:175], v[124:127]
	v_mfma_f32_16x16x32_bf16 v[120:123], v[156:159], v[172:175], v[120:123]
	v_mfma_f32_16x16x32_bf16 v[108:111], v[132:135], v[180:183], v[108:111]
	v_mfma_f32_16x16x32_bf16 v[104:107], v[156:159], v[180:183], v[104:107]
	v_mfma_f32_16x16x32_bf16 v[92:95], v[132:135], v[188:191], v[92:95]
	v_mfma_f32_16x16x32_bf16 v[88:91], v[156:159], v[188:191], v[88:91]
	v_mfma_f32_16x16x32_bf16 v[76:79], v[132:135], v[198:201], v[76:79]
	v_mfma_f32_16x16x32_bf16 v[72:75], v[156:159], v[198:201], v[72:75]
	s_barrier
	s_add_i32 s28, s57, s46
	v_lshl_add_u64 v[218:219], s[42:43], 0, v[142:143]
	s_mov_b32 m0, s28
	ds_read_b128 v[202:205], v169
	ds_read_b128 v[206:209], v169 offset:1024
	ds_read_b128 v[210:213], v169 offset:2048
	ds_read_b128 v[214:217], v169 offset:3072
	global_load_lds_dwordx4 v[218:219], off
	v_lshl_add_u64 v[220:221], s[42:43], 0, v[146:147]
	s_add_i32 m0, s28, 0x2000
	s_nop 0
	global_load_lds_dwordx4 v[220:221], off
	s_barrier
	s_waitcnt lgkmcnt(0)
	v_mfma_f32_16x16x32_bf16 v[116:119], v[202:205], v[160:163], 0
	v_mfma_f32_16x16x32_bf16 v[112:115], v[210:213], v[160:163], 0
	v_mfma_f32_16x16x32_bf16 v[100:103], v[202:205], v[176:179], 0
	v_mfma_f32_16x16x32_bf16 v[96:99], v[210:213], v[176:179], 0
	v_mfma_f32_16x16x32_bf16 v[84:87], v[202:205], v[184:187], 0
	v_mfma_f32_16x16x32_bf16 v[80:83], v[210:213], v[184:187], 0
	v_mfma_f32_16x16x32_bf16 v[68:71], v[202:205], v[194:197], 0
	v_mfma_f32_16x16x32_bf16 v[64:67], v[210:213], v[194:197], 0
	v_mfma_f32_16x16x32_bf16 v[116:119], v[206:209], v[172:175], v[116:119]
	v_mfma_f32_16x16x32_bf16 v[112:115], v[214:217], v[172:175], v[112:115]
	v_mfma_f32_16x16x32_bf16 v[100:103], v[206:209], v[180:183], v[100:103]
	v_mfma_f32_16x16x32_bf16 v[96:99], v[214:217], v[180:183], v[96:99]
	v_mfma_f32_16x16x32_bf16 v[84:87], v[206:209], v[188:191], v[84:87]
	v_mfma_f32_16x16x32_bf16 v[80:83], v[214:217], v[188:191], v[80:83]
	v_mfma_f32_16x16x32_bf16 v[68:71], v[206:209], v[198:201], v[68:71]
	v_mfma_f32_16x16x32_bf16 v[64:67], v[214:217], v[198:201], v[64:67]
	s_mov_b32 m0, s47
	v_lshl_add_u64 v[222:223], s[44:45], 0, v[140:141]
	s_barrier
	ds_read_b128 v[160:163], v168 offset:16384
	ds_read_b128 v[172:175], v168 offset:17408
	ds_read_b128 v[176:179], v168 offset:18432
	ds_read_b128 v[180:183], v168 offset:19456
	ds_read_b128 v[184:187], v168 offset:20480
	ds_read_b128 v[188:191], v168 offset:21504
	ds_read_b128 v[194:197], v168 offset:22528
	ds_read_b128 v[198:201], v168 offset:23552
	global_load_lds_dwordx4 v[222:223], off
	v_lshl_add_u64 v[224:225], s[44:45], 0, v[144:145]
	s_mov_b32 m0, s48
	s_nop 0
	global_load_lds_dwordx4 v[224:225], off
	s_barrier
	s_waitcnt lgkmcnt(0)
	v_mfma_f32_16x16x32_bf16 v[60:63], v[128:131], v[160:163], 0
	v_mfma_f32_16x16x32_bf16 v[56:59], v[136:139], v[160:163], 0
	v_mfma_f32_16x16x32_bf16 v[44:47], v[128:131], v[176:179], 0
	v_mfma_f32_16x16x32_bf16 v[40:43], v[136:139], v[176:179], 0
	v_mfma_f32_16x16x32_bf16 v[28:31], v[128:131], v[184:187], 0
	v_mfma_f32_16x16x32_bf16 v[24:27], v[136:139], v[184:187], 0
	v_mfma_f32_16x16x32_bf16 v[12:15], v[128:131], v[194:197], 0
	v_mfma_f32_16x16x32_bf16 v[8:11], v[136:139], v[194:197], 0
	v_mfma_f32_16x16x32_bf16 v[60:63], v[132:135], v[172:175], v[60:63]
	v_mfma_f32_16x16x32_bf16 v[56:59], v[156:159], v[172:175], v[56:59]
	v_mfma_f32_16x16x32_bf16 v[44:47], v[132:135], v[180:183], v[44:47]
	v_mfma_f32_16x16x32_bf16 v[40:43], v[156:159], v[180:183], v[40:43]
	v_mfma_f32_16x16x32_bf16 v[28:31], v[132:135], v[188:191], v[28:31]
	v_mfma_f32_16x16x32_bf16 v[24:27], v[156:159], v[188:191], v[24:27]
	v_mfma_f32_16x16x32_bf16 v[12:15], v[132:135], v[198:201], v[12:15]
	v_mfma_f32_16x16x32_bf16 v[8:11], v[156:159], v[198:201], v[8:11]
	s_barrier
	s_add_u32 s40, s42, 0x2c000
	s_addc_u32 s41, s43, 0
	s_add_i32 s28, s58, s46
	v_lshl_add_u64 v[128:129], s[40:41], 0, v[142:143]
	s_mov_b32 m0, s28
	s_nop 0
	global_load_lds_dwordx4 v[128:129], off
	v_lshl_add_u64 v[128:129], s[40:41], 0, v[146:147]
	s_add_i32 m0, s28, 0x2000
	s_nop 0
	global_load_lds_dwordx4 v[128:129], off
	s_waitcnt vmcnt(6)
	s_barrier
	v_mfma_f32_16x16x32_bf16 v[52:55], v[202:205], v[160:163], 0
	v_mfma_f32_16x16x32_bf16 v[48:51], v[210:213], v[160:163], 0
	v_mfma_f32_16x16x32_bf16 v[36:39], v[202:205], v[176:179], 0
	v_mfma_f32_16x16x32_bf16 v[32:35], v[210:213], v[176:179], 0
	v_mfma_f32_16x16x32_bf16 v[20:23], v[202:205], v[184:187], 0
	v_mfma_f32_16x16x32_bf16 v[16:19], v[210:213], v[184:187], 0
	v_mfma_f32_16x16x32_bf16 v[4:7], v[202:205], v[194:197], 0
	v_mfma_f32_16x16x32_bf16 v[0:3], v[210:213], v[194:197], 0
	v_mfma_f32_16x16x32_bf16 v[52:55], v[206:209], v[172:175], v[52:55]
	v_mfma_f32_16x16x32_bf16 v[48:51], v[214:217], v[172:175], v[48:51]
	v_mfma_f32_16x16x32_bf16 v[36:39], v[206:209], v[180:183], v[36:39]
	v_mfma_f32_16x16x32_bf16 v[32:35], v[214:217], v[180:183], v[32:35]
	v_mfma_f32_16x16x32_bf16 v[20:23], v[206:209], v[188:191], v[20:23]
	v_mfma_f32_16x16x32_bf16 v[16:19], v[214:217], v[188:191], v[16:19]
	v_mfma_f32_16x16x32_bf16 v[4:7], v[206:209], v[198:201], v[4:7]
	v_mfma_f32_16x16x32_bf16 v[0:3], v[214:217], v[198:201], v[0:3]
	s_add_i32 s28, 0, 0x18000
	v_add_u32_e32 v156, s28, v165
	s_barrier
	ds_read_b128 v[128:131], v156
	ds_read_b128 v[132:135], v156 offset:1024
	ds_read_b128 v[136:139], v156 offset:2048
	ds_read_b128 v[156:159], v156 offset:3072
	s_add_u32 s40, s44, 0xb0000
	s_addc_u32 s41, s45, 0
	s_mov_b32 m0, s49
	v_lshl_add_u64 v[202:203], s[40:41], 0, v[140:141]
	ds_read_b128 v[160:163], v168 offset:32768
	ds_read_b128 v[172:175], v168 offset:33792
	ds_read_b128 v[176:179], v168 offset:34816
	ds_read_b128 v[180:183], v168 offset:35840
	ds_read_b128 v[184:187], v168 offset:36864
	ds_read_b128 v[188:191], v168 offset:37888
	ds_read_b128 v[194:197], v168 offset:38912
	ds_read_b128 v[198:201], v168 offset:39936
	global_load_lds_dwordx4 v[202:203], off
	v_lshl_add_u64 v[202:203], s[40:41], 0, v[144:145]
	s_mov_b32 m0, s50
	s_nop 0
	global_load_lds_dwordx4 v[202:203], off
	s_waitcnt lgkmcnt(8)
	s_barrier
	s_waitcnt lgkmcnt(0)
	v_mfma_f32_16x16x32_bf16 v[124:127], v[128:131], v[160:163], v[124:127]
	v_mfma_f32_16x16x32_bf16 v[120:123], v[136:139], v[160:163], v[120:123]
	v_mfma_f32_16x16x32_bf16 v[108:111], v[128:131], v[176:179], v[108:111]
	v_mfma_f32_16x16x32_bf16 v[104:107], v[136:139], v[176:179], v[104:107]
	v_mfma_f32_16x16x32_bf16 v[92:95], v[128:131], v[184:187], v[92:95]
	v_mfma_f32_16x16x32_bf16 v[88:91], v[136:139], v[184:187], v[88:91]
	v_mfma_f32_16x16x32_bf16 v[76:79], v[128:131], v[194:197], v[76:79]
	v_mfma_f32_16x16x32_bf16 v[72:75], v[136:139], v[194:197], v[72:75]
	v_mfma_f32_16x16x32_bf16 v[124:127], v[132:135], v[172:175], v[124:127]
	v_mfma_f32_16x16x32_bf16 v[120:123], v[156:159], v[172:175], v[120:123]
	v_mfma_f32_16x16x32_bf16 v[108:111], v[132:135], v[180:183], v[108:111]
	v_mfma_f32_16x16x32_bf16 v[104:107], v[156:159], v[180:183], v[104:107]
	v_mfma_f32_16x16x32_bf16 v[92:95], v[132:135], v[188:191], v[92:95]
	v_mfma_f32_16x16x32_bf16 v[88:91], v[156:159], v[188:191], v[88:91]
	v_mfma_f32_16x16x32_bf16 v[76:79], v[132:135], v[198:201], v[76:79]
	v_mfma_f32_16x16x32_bf16 v[72:75], v[156:159], v[198:201], v[72:75]
	s_barrier
	s_add_i32 s29, 0, 0x1c000
	s_add_i32 s28, s28, s46
	v_add_u32_e32 v171, s29, v165
	v_lshl_add_u64 v[218:219], v[218:219], 0, s[36:37]
	s_mov_b32 m0, s28
	ds_read_b128 v[202:205], v171
	ds_read_b128 v[206:209], v171 offset:1024
	ds_read_b128 v[210:213], v171 offset:2048
	ds_read_b128 v[214:217], v171 offset:3072
	global_load_lds_dwordx4 v[218:219], off
	v_lshl_add_u64 v[218:219], v[220:221], 0, s[36:37]
	s_add_i32 m0, s28, 0x2000
	s_nop 0
	global_load_lds_dwordx4 v[218:219], off
	s_barrier
	s_waitcnt lgkmcnt(0)
	v_mfma_f32_16x16x32_bf16 v[116:119], v[202:205], v[160:163], v[116:119]
	v_mfma_f32_16x16x32_bf16 v[112:115], v[210:213], v[160:163], v[112:115]
	v_mfma_f32_16x16x32_bf16 v[100:103], v[202:205], v[176:179], v[100:103]
	v_mfma_f32_16x16x32_bf16 v[96:99], v[210:213], v[176:179], v[96:99]
	v_mfma_f32_16x16x32_bf16 v[84:87], v[202:205], v[184:187], v[84:87]
	v_mfma_f32_16x16x32_bf16 v[80:83], v[210:213], v[184:187], v[80:83]
	v_mfma_f32_16x16x32_bf16 v[68:71], v[202:205], v[194:197], v[68:71]
	v_mfma_f32_16x16x32_bf16 v[64:67], v[210:213], v[194:197], v[64:67]
	v_mfma_f32_16x16x32_bf16 v[116:119], v[206:209], v[172:175], v[116:119]
	v_mfma_f32_16x16x32_bf16 v[112:115], v[214:217], v[172:175], v[112:115]
	v_mfma_f32_16x16x32_bf16 v[100:103], v[206:209], v[180:183], v[100:103]
	v_mfma_f32_16x16x32_bf16 v[96:99], v[214:217], v[180:183], v[96:99]
	v_mfma_f32_16x16x32_bf16 v[84:87], v[206:209], v[188:191], v[84:87]
	v_mfma_f32_16x16x32_bf16 v[80:83], v[214:217], v[188:191], v[80:83]
	v_mfma_f32_16x16x32_bf16 v[68:71], v[206:209], v[198:201], v[68:71]
	v_mfma_f32_16x16x32_bf16 v[64:67], v[214:217], v[198:201], v[64:67]
	s_mov_b32 m0, s54
	v_lshl_add_u64 v[218:219], v[222:223], 0, s[36:37]
	s_barrier
	ds_read_b128 v[160:163], v168 offset:49152
	ds_read_b128 v[172:175], v168 offset:50176
	ds_read_b128 v[176:179], v168 offset:51200
	ds_read_b128 v[180:183], v168 offset:52224
	ds_read_b128 v[184:187], v168 offset:53248
	ds_read_b128 v[188:191], v168 offset:54272
	ds_read_b128 v[194:197], v168 offset:55296
	ds_read_b128 v[198:201], v168 offset:56320
	global_load_lds_dwordx4 v[218:219], off
	v_lshl_add_u64 v[218:219], v[224:225], 0, s[36:37]
	s_mov_b32 m0, s55
	s_nop 0
	global_load_lds_dwordx4 v[218:219], off
	s_barrier
	s_waitcnt lgkmcnt(0)
	v_mfma_f32_16x16x32_bf16 v[60:63], v[128:131], v[160:163], v[60:63]
	v_mfma_f32_16x16x32_bf16 v[56:59], v[136:139], v[160:163], v[56:59]
	v_mfma_f32_16x16x32_bf16 v[44:47], v[128:131], v[176:179], v[44:47]
	v_mfma_f32_16x16x32_bf16 v[40:43], v[136:139], v[176:179], v[40:43]
	v_mfma_f32_16x16x32_bf16 v[28:31], v[128:131], v[184:187], v[28:31]
	v_mfma_f32_16x16x32_bf16 v[24:27], v[136:139], v[184:187], v[24:27]
	v_mfma_f32_16x16x32_bf16 v[12:15], v[128:131], v[194:197], v[12:15]
	v_mfma_f32_16x16x32_bf16 v[8:11], v[136:139], v[194:197], v[8:11]
	v_mfma_f32_16x16x32_bf16 v[60:63], v[132:135], v[172:175], v[60:63]
	v_mfma_f32_16x16x32_bf16 v[56:59], v[156:159], v[172:175], v[56:59]
	v_mfma_f32_16x16x32_bf16 v[44:47], v[132:135], v[180:183], v[44:47]
	v_mfma_f32_16x16x32_bf16 v[40:43], v[156:159], v[180:183], v[40:43]
	v_mfma_f32_16x16x32_bf16 v[28:31], v[132:135], v[188:191], v[28:31]
	v_mfma_f32_16x16x32_bf16 v[24:27], v[156:159], v[188:191], v[24:27]
	v_mfma_f32_16x16x32_bf16 v[12:15], v[132:135], v[198:201], v[12:15]
	v_mfma_f32_16x16x32_bf16 v[8:11], v[156:159], v[198:201], v[8:11]
	s_barrier
	s_add_u32 s40, s42, 0x2c080
	s_addc_u32 s41, s43, 0
	s_add_i32 s28, s29, s46
	v_lshl_add_u64 v[128:129], s[40:41], 0, v[142:143]
	s_mov_b32 m0, s28
	s_nop 0
	global_load_lds_dwordx4 v[128:129], off
	v_lshl_add_u64 v[128:129], s[40:41], 0, v[146:147]
	s_add_i32 m0, s28, 0x2000
	s_nop 0
	global_load_lds_dwordx4 v[128:129], off
	s_waitcnt vmcnt(6)
	s_barrier
	v_mfma_f32_16x16x32_bf16 v[52:55], v[202:205], v[160:163], v[52:55]
	v_mfma_f32_16x16x32_bf16 v[48:51], v[210:213], v[160:163], v[48:51]
	v_mfma_f32_16x16x32_bf16 v[36:39], v[202:205], v[176:179], v[36:39]
	v_mfma_f32_16x16x32_bf16 v[32:35], v[210:213], v[176:179], v[32:35]
	v_mfma_f32_16x16x32_bf16 v[20:23], v[202:205], v[184:187], v[20:23]
	v_mfma_f32_16x16x32_bf16 v[16:19], v[210:213], v[184:187], v[16:19]
	v_mfma_f32_16x16x32_bf16 v[4:7], v[202:205], v[194:197], v[4:7]
	v_mfma_f32_16x16x32_bf16 v[0:3], v[210:213], v[194:197], v[0:3]
	v_mfma_f32_16x16x32_bf16 v[52:55], v[206:209], v[172:175], v[52:55]
	v_mfma_f32_16x16x32_bf16 v[48:51], v[214:217], v[172:175], v[48:51]
	v_mfma_f32_16x16x32_bf16 v[36:39], v[206:209], v[180:183], v[36:39]
	v_mfma_f32_16x16x32_bf16 v[32:35], v[214:217], v[180:183], v[32:35]
	v_mfma_f32_16x16x32_bf16 v[20:23], v[206:209], v[188:191], v[20:23]
	v_mfma_f32_16x16x32_bf16 v[16:19], v[214:217], v[188:191], v[16:19]
	v_mfma_f32_16x16x32_bf16 v[4:7], v[206:209], v[198:201], v[4:7]
	v_mfma_f32_16x16x32_bf16 v[0:3], v[214:217], v[198:201], v[0:3]
	s_add_i32 s65, s65, 2
	s_add_u32 s63, s63, 0x100
	s_addc_u32 s64, s64, 0
	s_cmp_gt_u32 s65, 41
	s_mov_b64 s[40:41], s[6:7]
	s_barrier
	s_cbranch_scc0 .LBB0_1169
